# hyena MFMA waves: gate rows staged by LDS-DMA at segment start + LDS reads instead of 46 scattered global loads; conv params hoisted
# speedup vs baseline: 1.0225x; 1.0225x over previous
.LBB0_651:
	v_readfirstlane_b32 s101, v0
	v_and_b32_e32 v253, 63, v0
	v_lshlrev_b32_e32 v253, 4, v253
	s_lshr_b32 s101, s101, 6
	s_add_i32 s98, s90, 0x200
	s_lshl_b32 s100, s101, 10
	s_lshl_b32 s98, s98, 12
	s_add_u32 s98, s98, s100
	s_add_u32 s98, s4, s98
	s_addc_u32 s99, s5, 0
	s_add_i32 s100, s100, 0x8d40
	s_mov_b32 m0, s100
	s_nop 0
	global_load_lds_dwordx4 v253, s[98:99]
	s_addk_i32 s100, 0x1190
	s_mov_b32 m0, s100
	s_add_u32 s98, s98, 0x600000
	s_addc_u32 s99, s99, 0
	global_load_lds_dwordx4 v253, s[98:99]
	s_addk_i32 s100, 0x1190
	s_mov_b32 m0, s100
	s_add_u32 s98, s98, 0x600000
	s_addc_u32 s99, s99, 0
	global_load_lds_dwordx4 v253, s[98:99]
	s_addk_i32 s100, 0x1190
	s_mov_b32 m0, s100
	s_add_u32 s98, s98, 0x600000
	s_addc_u32 s99, s99, 0
	global_load_lds_dwordx4 v253, s[98:99]
	s_addk_i32 s100, 0x1190
	s_mov_b32 m0, s100
	s_add_u32 s98, s98, 0x600000
	s_addc_u32 s99, s99, 0
	global_load_lds_dwordx4 v253, s[98:99]
	s_addk_i32 s100, 0x1190
	s_mov_b32 m0, s100
	s_add_u32 s98, s98, 0x600000
	s_addc_u32 s99, s99, 0
	global_load_lds_dwordx4 v253, s[98:99]
	s_addk_i32 s100, 0x1190
	s_mov_b32 m0, s100
	s_add_u32 s98, s98, 0x600000
	s_addc_u32 s99, s99, 0
	global_load_lds_dwordx4 v253, s[98:99]
	s_addk_i32 s100, 0x1190
	s_mov_b32 m0, s100
	s_add_u32 s98, s98, 0x600000
	s_addc_u32 s99, s99, 0
	global_load_lds_dwordx4 v253, s[98:99]
	global_load_dword v250, v137, s[92:93] offset:2048
	global_load_dword v253, v212, s[92:93]
	global_load_dword v254, v208, s[92:93] offset:2048
	global_load_dword v255, v137, s[94:95] offset:2048
	ds_read_b128 v[2:5], v218 offset:4032
	ds_read_b128 v[6:9], v218 offset:4064
	ds_read_b128 v[10:13], v1 offset:4224
	ds_read_b128 v[14:17], v1 offset:4256
	ds_read_b128 v[18:21], v218 offset:3968
	ds_read_b128 v[22:25], v218 offset:4000
	s_mov_b32 s10, 0
	s_waitcnt lgkmcnt(3)
	v_mfma_f32_32x32x16_bf16 v[50:65], v[2:5], v[10:13], 0
	ds_read_b128 v[2:5], v1 offset:4160
	ds_read_b128 v[10:13], v1 offset:4192
	s_waitcnt lgkmcnt(4)
	v_mfma_f32_32x32x16_bf16 v[50:65], v[6:9], v[14:17], v[50:65]
	s_waitcnt lgkmcnt(1)
	v_mfma_f32_32x32x16_bf16 v[50:65], v[18:21], v[2:5], v[50:65]
	ds_read_b128 v[6:9], v218 offset:3904
	ds_read_b128 v[14:17], v218 offset:3936
	ds_read_b128 v[2:5], v1 offset:4096
	ds_read_b128 v[18:21], v1 offset:4128
	s_waitcnt lgkmcnt(4)
	v_mfma_f32_32x32x16_bf16 v[50:65], v[22:25], v[10:13], v[50:65]
	s_waitcnt lgkmcnt(1)
	v_mfma_f32_32x32x16_bf16 v[50:65], v[6:9], v[2:5], v[50:65]
	ds_read_b128 v[10:13], v218 offset:3840
	ds_read_b128 v[22:25], v218 offset:3872
	ds_read_b128 v[2:5], v1 offset:4032
	ds_read_b128 v[6:9], v1 offset:4064
	s_waitcnt lgkmcnt(4)
	v_mfma_f32_32x32x16_bf16 v[50:65], v[14:17], v[18:21], v[50:65]
	s_waitcnt lgkmcnt(1)
	v_mfma_f32_32x32x16_bf16 v[50:65], v[10:13], v[2:5], v[50:65]
	ds_read_b128 v[14:17], v218 offset:3776
	ds_read_b128 v[18:21], v218 offset:3808
	ds_read_b128 v[2:5], v1 offset:3968
	ds_read_b128 v[10:13], v1 offset:4000
	ds_read_b128 v[26:29], v1 offset:4224
	ds_read_b128 v[30:33], v1 offset:4256
	s_waitcnt lgkmcnt(6)
	v_mfma_f32_32x32x16_bf16 v[50:65], v[22:25], v[6:9], v[50:65]
	s_waitcnt lgkmcnt(3)
	v_mfma_f32_32x32x16_bf16 v[50:65], v[14:17], v[2:5], v[50:65]
	ds_read_b128 v[2:5], v218 offset:3712
	ds_read_b128 v[6:9], v218 offset:3744
	s_waitcnt lgkmcnt(3)
	v_mfma_f32_32x32x16_bf16 v[34:49], v[14:17], v[26:29], 0
	ds_read_b128 v[14:17], v1 offset:3904
	ds_read_b128 v[22:25], v1 offset:3936
	ds_read_b128 v[26:29], v1 offset:4160
	ds_read_b128 v[70:73], v1 offset:4192
	v_mfma_f32_32x32x16_bf16 v[50:65], v[18:21], v[10:13], v[50:65]
	s_waitcnt lgkmcnt(6)
	v_mfma_f32_32x32x16_bf16 v[34:49], v[18:21], v[30:33], v[34:49]
	s_waitcnt lgkmcnt(3)
	v_mfma_f32_32x32x16_bf16 v[50:65], v[2:5], v[14:17], v[50:65]
	ds_read_b128 v[10:13], v218 offset:3648
	ds_read_b128 v[14:17], v218 offset:3680
	s_waitcnt lgkmcnt(3)
	v_mfma_f32_32x32x16_bf16 v[34:49], v[2:5], v[26:29], v[34:49]
	ds_read_b128 v[2:5], v1 offset:3840
	ds_read_b128 v[18:21], v1 offset:3872
	ds_read_b128 v[26:29], v1 offset:4096
	ds_read_b128 v[30:33], v1 offset:4128
	v_mfma_f32_32x32x16_bf16 v[50:65], v[6:9], v[22:25], v[50:65]
	s_waitcnt lgkmcnt(6)
	v_mfma_f32_32x32x16_bf16 v[34:49], v[6:9], v[70:73], v[34:49]
	s_waitcnt lgkmcnt(3)
	v_mfma_f32_32x32x16_bf16 v[50:65], v[10:13], v[2:5], v[50:65]
	ds_read_b128 v[2:5], v218 offset:3584
	ds_read_b128 v[6:9], v218 offset:3616
	s_waitcnt lgkmcnt(3)
	v_mfma_f32_32x32x16_bf16 v[34:49], v[10:13], v[26:29], v[34:49]
	ds_read_b128 v[10:13], v1 offset:3776
	ds_read_b128 v[22:25], v1 offset:3808
	ds_read_b128 v[26:29], v1 offset:4032
	ds_read_b128 v[70:73], v1 offset:4064
	v_mfma_f32_32x32x16_bf16 v[50:65], v[14:17], v[18:21], v[50:65]
	s_waitcnt lgkmcnt(6)
	v_mfma_f32_32x32x16_bf16 v[34:49], v[14:17], v[30:33], v[34:49]
	s_waitcnt lgkmcnt(3)
	v_mfma_f32_32x32x16_bf16 v[50:65], v[2:5], v[10:13], v[50:65]
	ds_read_b128 v[10:13], v218 offset:3520
	ds_read_b128 v[14:17], v218 offset:3552
	s_waitcnt lgkmcnt(3)
	v_mfma_f32_32x32x16_bf16 v[34:49], v[2:5], v[26:29], v[34:49]
	ds_read_b128 v[2:5], v1 offset:3712
	ds_read_b128 v[74:77], v1 offset:3744
	ds_read_b128 v[18:21], v1 offset:3968
	ds_read_b128 v[78:81], v1 offset:4000
	v_mfma_f32_32x32x16_bf16 v[50:65], v[6:9], v[22:25], v[50:65]
	ds_read_b128 v[26:29], v1 offset:4224
	ds_read_b128 v[82:85], v1 offset:4256
	s_waitcnt lgkmcnt(8)
	v_mfma_f32_32x32x16_bf16 v[34:49], v[6:9], v[70:73], v[34:49]
	s_waitcnt lgkmcnt(5)
	v_mfma_f32_32x32x16_bf16 v[50:65], v[10:13], v[2:5], v[50:65]
	ds_read_b128 v[2:5], v218 offset:3456
	ds_read_b128 v[6:9], v218 offset:3488
	s_waitcnt lgkmcnt(5)
	v_mfma_f32_32x32x16_bf16 v[34:49], v[10:13], v[18:21], v[34:49]
	s_waitcnt lgkmcnt(3)
	v_mfma_f32_32x32x16_bf16 v[18:33], v[10:13], v[26:29], 0
	ds_read_b128 v[70:73], v1 offset:3648
	ds_read_b128 v[86:89], v1 offset:3680
	ds_read_b128 v[10:13], v1 offset:3904
	ds_read_b128 v[90:93], v1 offset:3936
	v_mfma_f32_32x32x16_bf16 v[50:65], v[14:17], v[74:77], v[50:65]
	ds_read_b128 v[94:97], v1 offset:4160
	ds_read_b128 v[98:101], v1 offset:4192
	v_mfma_f32_32x32x16_bf16 v[34:49], v[14:17], v[78:81], v[34:49]
	s_waitcnt lgkmcnt(8)
	v_mfma_f32_32x32x16_bf16 v[18:33], v[14:17], v[82:85], v[18:33]
	s_waitcnt lgkmcnt(5)
	v_mfma_f32_32x32x16_bf16 v[50:65], v[2:5], v[70:73], v[50:65]
	ds_read_b128 v[14:17], v218 offset:3392
	ds_read_b128 v[70:73], v218 offset:3424
	s_waitcnt lgkmcnt(5)
	v_mfma_f32_32x32x16_bf16 v[34:49], v[2:5], v[10:13], v[34:49]
	s_waitcnt lgkmcnt(3)
	v_mfma_f32_32x32x16_bf16 v[18:33], v[2:5], v[94:97], v[18:33]
	ds_read_b128 v[10:13], v1 offset:3584
	ds_read_b128 v[74:77], v1 offset:3616
	ds_read_b128 v[2:5], v1 offset:3840
	ds_read_b128 v[78:81], v1 offset:3872
	v_mfma_f32_32x32x16_bf16 v[50:65], v[6:9], v[86:89], v[50:65]
	ds_read_b128 v[82:85], v1 offset:4096
	ds_read_b128 v[94:97], v1 offset:4128
	v_mfma_f32_32x32x16_bf16 v[34:49], v[6:9], v[90:93], v[34:49]
	s_waitcnt lgkmcnt(8)
	v_mfma_f32_32x32x16_bf16 v[18:33], v[6:9], v[98:101], v[18:33]
	s_waitcnt lgkmcnt(5)
	v_mfma_f32_32x32x16_bf16 v[50:65], v[14:17], v[10:13], v[50:65]
	ds_read_b128 v[6:9], v218 offset:3328
	ds_read_b128 v[10:13], v218 offset:3360
	s_waitcnt lgkmcnt(5)
	v_mfma_f32_32x32x16_bf16 v[34:49], v[14:17], v[2:5], v[34:49]
	s_waitcnt lgkmcnt(3)
	v_mfma_f32_32x32x16_bf16 v[18:33], v[14:17], v[82:85], v[18:33]
	ds_read_b128 v[2:5], v1 offset:3520
	ds_read_b128 v[90:93], v1 offset:3552
	ds_read_b128 v[14:17], v1 offset:3776
	ds_read_b128 v[110:113], v1 offset:3808
	v_mfma_f32_32x32x16_bf16 v[50:65], v[70:73], v[74:77], v[50:65]
	ds_read_b128 v[82:85], v1 offset:4032
	ds_read_b128 v[114:117], v1 offset:4064
	v_mfma_f32_32x32x16_bf16 v[34:49], v[70:73], v[78:81], v[34:49]
	s_waitcnt lgkmcnt(8)
	v_mfma_f32_32x32x16_bf16 v[18:33], v[70:73], v[94:97], v[18:33]
	s_waitcnt lgkmcnt(5)
	v_mfma_f32_32x32x16_bf16 v[50:65], v[6:9], v[2:5], v[50:65]
	ds_read_b128 v[74:77], v218 offset:3264
	ds_read_b128 v[70:73], v218 offset:3296
	s_waitcnt lgkmcnt(5)
	v_mfma_f32_32x32x16_bf16 v[34:49], v[6:9], v[14:17], v[34:49]
	s_waitcnt lgkmcnt(3)
	v_mfma_f32_32x32x16_bf16 v[18:33], v[6:9], v[82:85], v[18:33]
	ds_read_b128 v[106:109], v1 offset:3456
	ds_read_b128 v[78:81], v1 offset:3488
	ds_read_b128 v[94:97], v1 offset:3712
	ds_read_b128 v[82:85], v1 offset:3744
	v_mfma_f32_32x32x16_bf16 v[50:65], v[10:13], v[90:93], v[50:65]
	ds_read_b128 v[98:101], v1 offset:3968
	ds_read_b128 v[86:89], v1 offset:4000
	v_mfma_f32_32x32x16_bf16 v[34:49], v[10:13], v[110:113], v[34:49]
	ds_read_b128 v[102:105], v1 offset:4224
	ds_read_b128 v[90:93], v1 offset:4256
	s_waitcnt lgkmcnt(10)
	v_mfma_f32_32x32x16_bf16 v[18:33], v[10:13], v[114:117], v[18:33]
	v_mov_b32_e32 v2, 0
	v_mov_b32_e32 v3, v2
	v_mov_b32_e32 v4, v2
	v_mov_b32_e32 v5, v2
	v_mov_b32_e32 v6, v2
	v_mov_b32_e32 v7, v2
	v_mov_b32_e32 v8, v2
	v_mov_b32_e32 v9, v2
	v_mov_b32_e32 v10, v2
	v_mov_b32_e32 v11, v2
	v_mov_b32_e32 v12, v2
	v_mov_b32_e32 v13, v2
	v_mov_b32_e32 v14, v2
	v_mov_b32_e32 v15, v2
	v_mov_b32_e32 v16, v2
	v_mov_b32_e32 v17, v2
.LBB0_652:
	s_waitcnt lgkmcnt(7)
	v_mfma_f32_32x32x16_bf16 v[50:65], v[74:77], v[106:109], v[50:65]
	v_add_u32_e32 v106, s10, v179
	v_add_u32_e32 v107, 0x12580, v106
	v_add_u32_e32 v108, 0x125a0, v106
	ds_read_b128 v[110:113], v107
	ds_read_b128 v[114:117], v108
	v_add_u32_e32 v136, s10, v206
	s_waitcnt lgkmcnt(7)
	v_mfma_f32_32x32x16_bf16 v[34:49], v[74:77], v[94:97], v[34:49]
	s_waitcnt lgkmcnt(5)
	v_mfma_f32_32x32x16_bf16 v[18:33], v[74:77], v[98:101], v[18:33]
	ds_read_b128 v[94:97], v136
	ds_read_b128 v[118:121], v136 offset:32
	s_waitcnt lgkmcnt(5)
	v_mfma_f32_32x32x16_bf16 v[2:17], v[74:77], v[102:105], v[2:17]
	ds_read_b128 v[98:101], v136 offset:256
	ds_read_b128 v[122:125], v136 offset:288
	v_mfma_f32_32x32x16_bf16 v[50:65], v[70:73], v[78:81], v[50:65]
	ds_read_b128 v[102:105], v136 offset:512
	ds_read_b128 v[126:129], v136 offset:544
	v_mfma_f32_32x32x16_bf16 v[34:49], v[70:73], v[82:85], v[34:49]
	ds_read_b128 v[130:133], v136 offset:768
	ds_read_b128 v[198:201], v136 offset:800
	v_mfma_f32_32x32x16_bf16 v[18:33], v[70:73], v[86:89], v[18:33]
	s_waitcnt lgkmcnt(10)
	v_mfma_f32_32x32x16_bf16 v[2:17], v[70:73], v[90:93], v[2:17]
	s_waitcnt lgkmcnt(7)
	v_mfma_f32_32x32x16_bf16 v[50:65], v[110:113], v[94:97], v[50:65]
	v_add_u32_e32 v70, 0x12540, v106
	v_add_u32_e32 v71, 0x12560, v106
	ds_read_b128 v[74:77], v70
	ds_read_b128 v[70:73], v71
	s_waitcnt lgkmcnt(7)
	v_mfma_f32_32x32x16_bf16 v[34:49], v[110:113], v[98:101], v[34:49]
	s_waitcnt lgkmcnt(5)
	v_mfma_f32_32x32x16_bf16 v[18:33], v[110:113], v[102:105], v[18:33]
	v_subrev_u32_e32 v78, 64, v136
	ds_read_b128 v[106:109], v78
	ds_read_b128 v[78:81], v78 offset:32
	s_waitcnt lgkmcnt(5)
	v_mfma_f32_32x32x16_bf16 v[2:17], v[110:113], v[130:133], v[2:17]
	ds_read_b128 v[94:97], v136 offset:192
	ds_read_b128 v[82:85], v136 offset:224
	v_mfma_f32_32x32x16_bf16 v[50:65], v[114:117], v[118:121], v[50:65]
	ds_read_b128 v[98:101], v136 offset:448
	ds_read_b128 v[86:89], v136 offset:480
	v_mfma_f32_32x32x16_bf16 v[34:49], v[114:117], v[122:125], v[34:49]
	ds_read_b128 v[102:105], v136 offset:704
	ds_read_b128 v[90:93], v136 offset:736
	v_mfma_f32_32x32x16_bf16 v[18:33], v[114:117], v[126:129], v[18:33]
	s_waitcnt lgkmcnt(10)
	v_mfma_f32_32x32x16_bf16 v[2:17], v[114:117], v[198:201], v[2:17]
	s_addk_i32 s10, 0xff80
	s_cmpk_eq_i32 s10, 0xf280
	s_cbranch_scc0 .LBB0_652
	v_add_u32_e32 v230, s10, v179
	s_add_i32 s10, s90, 0x200
	s_ashr_i32 s11, s10, 31
	v_lshl_add_u64 v[110:111], v[150:151], 0, s[10:11]
	v_lshlrev_b64 v[110:111], 12, v[110:111]
	v_lshl_add_u64 v[242:243], s[4:5], 0, v[110:111]
	v_lshlrev_b32_e32 v136, 1, v152
	v_lshl_add_u64 v[110:111], v[242:243], 0, v[136:137]
	v_lshlrev_b32_e32 v136, 1, v154
	v_lshl_add_u64 v[112:113], v[242:243], 0, v[136:137]
	v_mov_b32_e32 v171, v137
	v_mov_b32_e32 v173, v137
	s_waitcnt vmcnt(0)
	v_bfe_u32 v136, v0, 2, 3
	v_mul_u32_u24_e32 v136, 0x1190, v136
	v_lshl_add_u32 v136, v152, 1, v136
	ds_read_b64 v[204:205], v136 offset:36160
	global_load_ushort v226, v[112:113], off offset:-2
	ds_read_u16 v227, v136 offset:36168
	ds_read_b64 v[202:203], v136 offset:36176
	ds_read_u16 v225, v136 offset:36174
	ds_read_u16 v228, v136 offset:36184
	ds_read_b64 v[200:201], v136 offset:36192
	ds_read_u16 v224, v136 offset:36190
	ds_read_u16 v229, v136 offset:36200
	ds_read_b64 v[198:199], v136 offset:36208
	ds_read_u16 v223, v136 offset:36206
	ds_read_u16 v231, v136 offset:36216
	v_lshl_add_u64 v[110:111], v[242:243], 0, v[170:171]
	v_lshl_add_u64 v[112:113], v[242:243], 0, v[172:173]
	v_mov_b32_e32 v175, v137
	ds_read_b64 v[132:133], v136 offset:36416
	ds_read_u16 v222, v136 offset:36414
	ds_read_u16 v232, v136 offset:36424
	ds_read_b64 v[130:131], v136 offset:36432
	ds_read_u16 v221, v136 offset:36430
	ds_read_u16 v233, v136 offset:36440
	ds_read_b64 v[128:129], v136 offset:36448
	ds_read_u16 v220, v136 offset:36446
	v_lshl_add_u64 v[112:113], v[242:243], 0, v[174:175]
	v_mov_b32_e32 v177, v137
	ds_read_u16 v234, v136 offset:36456
	ds_read_b64 v[126:127], v136 offset:36464
	ds_read_u16 v219, v136 offset:36462
	v_lshl_add_u64 v[110:111], v[242:243], 0, v[176:177]
	v_mov_b32_e32 v181, v137
	v_mov_b32_e32 v183, v137
	ds_read_u16 v235, v136 offset:36472
	v_lshl_add_u64 v[110:111], v[242:243], 0, v[180:181]
	v_lshl_add_u64 v[112:113], v[242:243], 0, v[182:183]
	v_mov_b32_e32 v185, v137
	ds_read_b64 v[124:125], v136 offset:36672
	ds_read_u16 v197, v136 offset:36670
	ds_read_u16 v236, v136 offset:36680
	ds_read_b64 v[122:123], v136 offset:36688
	ds_read_u16 v181, v136 offset:36686
	ds_read_u16 v183, v136 offset:36696
	ds_read_b64 v[120:121], v136 offset:36704
	ds_read_u16 v177, v136 offset:36702
	v_lshl_add_u64 v[112:113], v[242:243], 0, v[184:185]
	v_mov_b32_e32 v187, v137
	v_mov_b32_e32 v189, v137
	ds_read_u16 v185, v136 offset:36712
	ds_read_b64 v[118:119], v136 offset:36720
	ds_read_u16 v175, v136 offset:36718
	v_lshl_add_u64 v[110:111], v[242:243], 0, v[186:187]
	v_lshl_add_u64 v[244:245], v[242:243], 0, v[188:189]
	v_mov_b32_e32 v191, v137
	ds_read_u16 v187, v136 offset:36728
	ds_read_b64 v[116:117], v136 offset:36928
	ds_read_u16 v173, v136 offset:36926
	ds_read_u16 v189, v136 offset:36936
	ds_read_b64 v[114:115], v136 offset:36944
	ds_read_u16 v171, v136 offset:36942
	v_lshl_add_u64 v[110:111], v[242:243], 0, v[190:191]
	v_mov_b32_e32 v193, v137
	ds_read_u16 v191, v136 offset:36952
	ds_read_b64 v[112:113], v136 offset:36960
	ds_read_u16 v169, v136 offset:36958
	v_lshl_add_u64 v[110:111], v[242:243], 0, v[192:193]
	v_mov_b32_e32 v195, v137
	ds_read_u16 v193, v136 offset:36968
	s_nop 0
	ds_read_b64 v[110:111], v136 offset:36976
	ds_read_u16 v136, v136 offset:36974
	v_lshl_add_u64 v[242:243], v[242:243], 0, v[194:195]
	global_load_ushort v195, v[242:243], off offset:8
	s_waitcnt lgkmcnt(7)
	v_mfma_f32_32x32x16_bf16 v[50:65], v[74:77], v[106:109], v[50:65]
	v_add_u32_e32 v237, 0x12580, v230
	ds_read_b128 v[242:245], v237
	v_add_u32_e32 v237, 0x125a0, v230
	ds_read_b128 v[246:249], v237
	s_waitcnt lgkmcnt(7)
	v_mfma_f32_32x32x16_bf16 v[34:49], v[74:77], v[94:97], v[34:49]
	s_waitcnt lgkmcnt(5)
	v_mfma_f32_32x32x16_bf16 v[18:33], v[74:77], v[98:101], v[18:33]
	s_waitcnt lgkmcnt(3)
	v_mfma_f32_32x32x16_bf16 v[2:17], v[74:77], v[102:105], v[2:17]
	ds_read_b128 v[94:97], v1 offset:192
	ds_read_b128 v[98:101], v1 offset:224
	v_mfma_f32_32x32x16_bf16 v[50:65], v[70:73], v[78:81], v[50:65]
	ds_read_b128 v[74:77], v1 offset:448
	ds_read_b128 v[102:105], v1 offset:480
	v_mfma_f32_32x32x16_bf16 v[34:49], v[70:73], v[82:85], v[34:49]
	ds_read_b128 v[78:81], v1 offset:704
	ds_read_b128 v[106:109], v1 offset:736
	v_mfma_f32_32x32x16_bf16 v[18:33], v[70:73], v[86:89], v[18:33]
	s_waitcnt lgkmcnt(8)
	v_mfma_f32_32x32x16_bf16 v[2:17], v[70:73], v[90:93], v[2:17]
	s_waitcnt lgkmcnt(5)
	v_mfma_f32_32x32x16_bf16 v[34:49], v[242:245], v[94:97], v[34:49]
	v_add_u32_e32 v70, 0x12540, v230
	v_add_u32_e32 v82, 0x12560, v230
	ds_read_b128 v[70:73], v70
	ds_read_b128 v[82:85], v82
	s_waitcnt lgkmcnt(5)
	v_mfma_f32_32x32x16_bf16 v[18:33], v[242:245], v[74:77], v[18:33]
	s_waitcnt lgkmcnt(3)
	v_mfma_f32_32x32x16_bf16 v[2:17], v[242:245], v[78:81], v[2:17]
	ds_read_b128 v[74:77], v1 offset:128
	ds_read_b128 v[86:89], v1 offset:160
	ds_read_b128 v[78:81], v1 offset:384
	ds_read_b128 v[90:93], v1 offset:416
	v_mfma_f32_32x32x16_bf16 v[34:49], v[246:249], v[98:101], v[34:49]
	ds_read_b128 v[94:97], v1 offset:640
	ds_read_b128 v[242:245], v1 offset:672
	v_mfma_f32_32x32x16_bf16 v[18:33], v[246:249], v[102:105], v[18:33]
	s_waitcnt lgkmcnt(8)
	v_mfma_f32_32x32x16_bf16 v[2:17], v[246:249], v[106:109], v[2:17]
	s_waitcnt lgkmcnt(5)
	v_mfma_f32_32x32x16_bf16 v[34:49], v[70:73], v[74:77], v[34:49]
	v_add_u32_e32 v98, 0x12500, v230
	v_add_u32_e32 v102, 0x12520, v230
	ds_read_b128 v[98:101], v98
	ds_read_b128 v[102:105], v102
	s_waitcnt lgkmcnt(5)
	v_mfma_f32_32x32x16_bf16 v[18:33], v[70:73], v[78:81], v[18:33]
	s_waitcnt lgkmcnt(3)
	v_mfma_f32_32x32x16_bf16 v[2:17], v[70:73], v[94:97], v[2:17]
	ds_read_b128 v[74:77], v1 offset:64
	ds_read_b128 v[78:81], v1 offset:96
	ds_read_b128 v[70:73], v1 offset:320
	ds_read_b128 v[94:97], v1 offset:352
	v_mfma_f32_32x32x16_bf16 v[34:49], v[82:85], v[86:89], v[34:49]
	ds_read_b128 v[106:109], v1 offset:576
	ds_read_b128 v[246:249], v1 offset:608
	v_mfma_f32_32x32x16_bf16 v[18:33], v[82:85], v[90:93], v[18:33]
	s_waitcnt lgkmcnt(8)
	v_mfma_f32_32x32x16_bf16 v[2:17], v[82:85], v[242:245], v[2:17]
	s_waitcnt lgkmcnt(5)
	v_mfma_f32_32x32x16_bf16 v[34:49], v[98:101], v[74:77], v[34:49]
	v_add_u32_e32 v82, 0x124c0, v230
	v_add_u32_e32 v86, 0x124e0, v230
	ds_read_b128 v[82:85], v82
	ds_read_b128 v[86:89], v86
	s_waitcnt lgkmcnt(5)
	v_mfma_f32_32x32x16_bf16 v[18:33], v[98:101], v[70:73], v[18:33]
	s_waitcnt lgkmcnt(3)
	v_mfma_f32_32x32x16_bf16 v[2:17], v[98:101], v[106:109], v[2:17]
	ds_read_b128 v[70:73], v1
	ds_read_b128 v[74:77], v1 offset:32
	ds_read_b128 v[90:93], v1 offset:256
	ds_read_b128 v[98:101], v1 offset:288
	v_mfma_f32_32x32x16_bf16 v[34:49], v[102:105], v[78:81], v[34:49]
	ds_read_b128 v[106:109], v1 offset:512
	ds_read_b128 v[242:245], v1 offset:544
	v_mfma_f32_32x32x16_bf16 v[18:33], v[102:105], v[94:97], v[18:33]
	s_waitcnt lgkmcnt(8)
	v_mfma_f32_32x32x16_bf16 v[2:17], v[102:105], v[246:249], v[2:17]
	s_waitcnt lgkmcnt(5)
	v_mfma_f32_32x32x16_bf16 v[34:49], v[82:85], v[70:73], v[34:49]
	v_add_u32_e32 v78, 0x12480, v230
	v_add_u32_e32 v94, 0x124a0, v230
	ds_read_b128 v[78:81], v78
	ds_read_b128 v[94:97], v94
	s_waitcnt lgkmcnt(5)
	v_mfma_f32_32x32x16_bf16 v[18:33], v[82:85], v[90:93], v[18:33]
	s_waitcnt lgkmcnt(3)
	v_mfma_f32_32x32x16_bf16 v[2:17], v[82:85], v[106:109], v[2:17]
	ds_read_b128 v[70:73], v1 offset:192
	ds_read_b128 v[82:85], v1 offset:224
	v_mfma_f32_32x32x16_bf16 v[34:49], v[86:89], v[74:77], v[34:49]
	ds_read_b128 v[90:93], v1 offset:448
	ds_read_b128 v[102:105], v1 offset:480
	v_mfma_f32_32x32x16_bf16 v[18:33], v[86:89], v[98:101], v[18:33]
	s_waitcnt lgkmcnt(6)
	v_mfma_f32_32x32x16_bf16 v[2:17], v[86:89], v[242:245], v[2:17]
	v_add_u32_e32 v74, 0x12440, v230
	v_add_u32_e32 v86, 0x12460, v230
	ds_read_b128 v[74:77], v74
	ds_read_b128 v[86:89], v86
	s_waitcnt lgkmcnt(5)
	v_mfma_f32_32x32x16_bf16 v[18:33], v[78:81], v[70:73], v[18:33]
	s_waitcnt lgkmcnt(3)
	v_mfma_f32_32x32x16_bf16 v[2:17], v[78:81], v[90:93], v[2:17]
	ds_read_b128 v[70:73], v1 offset:128
	ds_read_b128 v[78:81], v1 offset:160
	ds_read_b128 v[90:93], v1 offset:384
	ds_read_b128 v[98:101], v1 offset:416
	v_mfma_f32_32x32x16_bf16 v[18:33], v[94:97], v[82:85], v[18:33]
	s_waitcnt lgkmcnt(6)
	v_mfma_f32_32x32x16_bf16 v[2:17], v[94:97], v[102:105], v[2:17]
	v_add_u32_e32 v82, 0x12400, v230
	v_add_u32_e32 v94, 0x12420, v230
	ds_read_b128 v[82:85], v82
	ds_read_b128 v[94:97], v94
	s_waitcnt lgkmcnt(5)
	v_mfma_f32_32x32x16_bf16 v[18:33], v[74:77], v[70:73], v[18:33]
	s_waitcnt lgkmcnt(3)
	v_mfma_f32_32x32x16_bf16 v[2:17], v[74:77], v[90:93], v[2:17]
	ds_read_b128 v[70:73], v1 offset:64
	ds_read_b128 v[74:77], v1 offset:96
	ds_read_b128 v[90:93], v1 offset:320
	ds_read_b128 v[102:105], v1 offset:352
	v_mfma_f32_32x32x16_bf16 v[18:33], v[86:89], v[78:81], v[18:33]
	s_waitcnt lgkmcnt(6)
	v_mfma_f32_32x32x16_bf16 v[2:17], v[86:89], v[98:101], v[2:17]
	v_add_u32_e32 v78, 0x123c0, v230
	v_add_u32_e32 v86, 0x123e0, v230
	ds_read_b128 v[78:81], v78
	ds_read_b128 v[86:89], v86
	s_waitcnt lgkmcnt(5)
	v_mfma_f32_32x32x16_bf16 v[18:33], v[82:85], v[70:73], v[18:33]
	s_waitcnt lgkmcnt(3)
	v_mfma_f32_32x32x16_bf16 v[2:17], v[82:85], v[90:93], v[2:17]
	ds_read_b128 v[70:73], v1
	ds_read_b128 v[82:85], v1 offset:32
	ds_read_b128 v[90:93], v1 offset:256
	ds_read_b128 v[98:101], v1 offset:288
	v_mfma_f32_32x32x16_bf16 v[18:33], v[94:97], v[74:77], v[18:33]
	s_waitcnt lgkmcnt(6)
	v_mfma_f32_32x32x16_bf16 v[2:17], v[94:97], v[102:105], v[2:17]
	v_add_u32_e32 v74, 0x12380, v230
	v_add_u32_e32 v94, 0x123a0, v230
	ds_read_b128 v[74:77], v74
	ds_read_b128 v[94:97], v94
	s_waitcnt lgkmcnt(5)
	v_mfma_f32_32x32x16_bf16 v[18:33], v[78:81], v[70:73], v[18:33]
	s_waitcnt lgkmcnt(3)
	v_mfma_f32_32x32x16_bf16 v[2:17], v[78:81], v[90:93], v[2:17]
	ds_read_b128 v[70:73], v1 offset:192
	ds_read_b128 v[78:81], v1 offset:224
	v_mfma_f32_32x32x16_bf16 v[18:33], v[86:89], v[82:85], v[18:33]
	s_waitcnt lgkmcnt(4)
	v_mfma_f32_32x32x16_bf16 v[2:17], v[86:89], v[98:101], v[2:17]
	v_add_u32_e32 v82, 0x12340, v230
	v_add_u32_e32 v86, 0x12360, v230
	ds_read_b128 v[82:85], v82
	ds_read_b128 v[86:89], v86
	s_waitcnt lgkmcnt(3)
	v_mfma_f32_32x32x16_bf16 v[2:17], v[74:77], v[70:73], v[2:17]
	ds_read_b128 v[70:73], v1 offset:128
	ds_read_b128 v[74:77], v1 offset:160
	s_waitcnt lgkmcnt(4)
	v_mfma_f32_32x32x16_bf16 v[2:17], v[94:97], v[78:81], v[2:17]
	v_add_u32_e32 v78, 0x12300, v230
	v_add_u32_e32 v90, 0x12320, v230
	ds_read_b128 v[78:81], v78
	ds_read_b128 v[90:93], v90
	s_waitcnt lgkmcnt(3)
	v_mfma_f32_32x32x16_bf16 v[2:17], v[82:85], v[70:73], v[2:17]
	ds_read_b128 v[70:73], v1 offset:64
	ds_read_b128 v[82:85], v1 offset:96
	s_waitcnt lgkmcnt(4)
	v_mfma_f32_32x32x16_bf16 v[2:17], v[86:89], v[74:77], v[2:17]
	v_add_u32_e32 v74, 0x122c0, v230
	v_add_u32_e32 v86, 0x122e0, v230
	ds_read_b128 v[74:77], v74
	ds_read_b128 v[86:89], v86
	s_waitcnt lgkmcnt(3)
	v_mfma_f32_32x32x16_bf16 v[2:17], v[78:81], v[70:73], v[2:17]
	ds_read_b128 v[70:73], v1
	ds_read_b128 v[78:81], v1 offset:32
	s_waitcnt lgkmcnt(4)
	v_mfma_f32_32x32x16_bf16 v[2:17], v[90:93], v[82:85], v[2:17]
	s_waitcnt lgkmcnt(1)
	v_mfma_f32_32x32x16_bf16 v[2:17], v[74:77], v[70:73], v[2:17]
	s_and_b64 vcc, exec, s[70:71]
	s_waitcnt lgkmcnt(0)
	v_mfma_f32_32x32x16_bf16 v[2:17], v[86:89], v[78:81], v[2:17]
	s_cbranch_vccz .LBB0_655
	s_waitcnt vmcnt(0)
	v_mov_b32_e32 v72, v250
	v_mov_b32_e32 v76, v253
	v_mov_b32_e32 v74, v254
	v_mov_b32_e32 v82, v255
	v_lshlrev_b32_e32 v70, 16, v195
	v_cndmask_b32_e64 v71, 0, v70, s[76:77]
	v_lshlrev_b32_e32 v70, 16, v187
	v_cndmask_b32_e64 v87, 0, v70, s[78:79]
	v_lshlrev_b32_e32 v70, 16, v226
	v_lshlrev_b32_e32 v105, 16, v229
	v_lshlrev_b32_e32 v107, 16, v228
	v_lshlrev_b32_e32 v109, 16, v227
	v_cndmask_b32_e64 v226, v70, 0, s[12:13]
	v_lshlrev_b32_e32 v227, 16, v204
	v_and_b32_e32 v229, 16, v205
	v_and_b32_e32 v228, 0xffff0000, v204
	v_mov_b32_e32 v204, v228
	v_pk_mov_b32 v[228:229], v[226:227], v[228:229] op_sel:[1,0]
	v_and_b32_e32 v108, 0xffff0000, v205
	v_lshlrev_b32_e32 v205, 16, v205
	v_lshlrev_b32_e32 v103, 16, v231
	v_pk_mov_b32 v[230:231], v[204:205], v[108:109] op_sel:[1,0]
	v_and_b32_e32 v106, 0xffff0000, v203
	v_add_u32_e32 v70, 0x8800, v213
	v_and_b32_e32 v104, 0xffff0000, v201
	v_and_b32_e32 v102, 0xffff0000, v199
	v_lshlrev_b32_e32 v101, 16, v232
	v_and_b32_e32 v100, 0xffff0000, v133
	v_lshlrev_b32_e32 v99, 16, v233
	v_and_b32_e32 v98, 0xffff0000, v131
	v_lshlrev_b32_e32 v97, 16, v234
	v_and_b32_e32 v96, 0xffff0000, v129
	v_lshlrev_b32_e32 v95, 16, v235
	v_and_b32_e32 v94, 0xffff0000, v127
	v_lshlrev_b32_e32 v93, 16, v236
	v_and_b32_e32 v92, 0xffff0000, v125
	v_lshlrev_b32_e32 v91, 16, v183
	v_and_b32_e32 v90, 0xffff0000, v123
	v_lshlrev_b32_e32 v89, 16, v185
	v_and_b32_e32 v88, 0xffff0000, v121
	v_and_b32_e32 v86, 0xffff0000, v119
	v_lshlrev_b32_e32 v85, 16, v189
	v_and_b32_e32 v84, 0xffff0000, v117
	v_lshlrev_b32_e32 v81, 16, v191
	v_and_b32_e32 v80, 0xffff0000, v115
	v_lshlrev_b32_e32 v79, 16, v193
	v_and_b32_e32 v78, 0xffff0000, v113
	s_waitcnt vmcnt(2)
	v_pk_mul_f32 v[228:229], v[76:77], v[228:229] op_sel_hi:[0,1]
	v_pk_fma_f32 v[226:227], v[72:73], v[226:227], v[228:229] op_sel_hi:[0,1,1]
	s_waitcnt vmcnt(1)
	v_pk_fma_f32 v[226:227], v[74:75], v[204:205], v[226:227] op_sel_hi:[0,1,1]
	s_waitcnt vmcnt(0)
	v_pk_add_f32 v[226:227], v[82:83], v[226:227] op_sel_hi:[0,1]
	v_pk_mul_f32 v[50:51], v[50:51], v[226:227]
	v_pk_mul_f32 v[226:227], v[76:77], v[230:231] op_sel_hi:[0,1]
	v_pk_fma_f32 v[204:205], v[72:73], v[204:205], v[226:227] op_sel_hi:[0,1,1]
	v_pk_fma_f32 v[108:109], v[74:75], v[108:109], v[204:205] op_sel_hi:[0,1,1]
	v_pk_add_f32 v[108:109], v[82:83], v[108:109] op_sel_hi:[0,1]
	v_pk_mul_f32 v[52:53], v[52:53], v[108:109]
	v_cvt_pk_bf16_f32 v50, v50, v51
	v_cvt_pk_bf16_f32 v51, v52, v53
	v_and_b32_e32 v53, 16, v203
	v_and_b32_e32 v52, 0xffff0000, v202
	v_lshlrev_b32_e32 v109, 16, v203
	v_lshlrev_b32_e32 v203, 16, v202
	v_lshlrev_b32_e32 v202, 16, v225
	v_mov_b32_e32 v108, v52
	v_pk_mov_b32 v[52:53], v[202:203], v[52:53] op_sel:[1,0]
	v_pk_mov_b32 v[204:205], v[108:109], v[106:107] op_sel:[1,0]
	v_pk_mul_f32 v[52:53], v[76:77], v[52:53] op_sel_hi:[0,1]
	v_pk_fma_f32 v[52:53], v[72:73], v[202:203], v[52:53] op_sel_hi:[0,1,1]
	v_pk_fma_f32 v[52:53], v[74:75], v[108:109], v[52:53] op_sel_hi:[0,1,1]
	v_pk_add_f32 v[52:53], v[82:83], v[52:53] op_sel_hi:[0,1]
	v_pk_mul_f32 v[52:53], v[54:55], v[52:53]
	v_pk_mul_f32 v[54:55], v[76:77], v[204:205] op_sel_hi:[0,1]
	v_pk_fma_f32 v[54:55], v[72:73], v[108:109], v[54:55] op_sel_hi:[0,1,1]
	v_pk_fma_f32 v[54:55], v[74:75], v[106:107], v[54:55] op_sel_hi:[0,1,1]
	v_pk_add_f32 v[54:55], v[82:83], v[54:55] op_sel_hi:[0,1]
	v_pk_mul_f32 v[54:55], v[56:57], v[54:55]
	v_cvt_pk_bf16_f32 v52, v52, v53
	v_cvt_pk_bf16_f32 v53, v54, v55
	ds_write2_b64 v70, v[50:51], v[52:53] offset0:168 offset1:170
	v_and_b32_e32 v51, 16, v201
	v_and_b32_e32 v50, 0xffff0000, v200
	v_lshlrev_b32_e32 v57, 16, v200
	v_lshlrev_b32_e32 v56, 16, v224
	v_lshlrev_b32_e32 v53, 16, v201
	v_mov_b32_e32 v52, v50
	v_pk_mov_b32 v[50:51], v[56:57], v[50:51] op_sel:[1,0]
	v_pk_mov_b32 v[54:55], v[52:53], v[104:105] op_sel:[1,0]
	v_pk_mul_f32 v[50:51], v[76:77], v[50:51] op_sel_hi:[0,1]
	v_pk_fma_f32 v[50:51], v[72:73], v[56:57], v[50:51] op_sel_hi:[0,1,1]
	v_pk_mul_f32 v[54:55], v[76:77], v[54:55] op_sel_hi:[0,1]
	v_pk_fma_f32 v[50:51], v[74:75], v[52:53], v[50:51] op_sel_hi:[0,1,1]
	v_pk_fma_f32 v[52:53], v[72:73], v[52:53], v[54:55] op_sel_hi:[0,1,1]
	v_pk_fma_f32 v[52:53], v[74:75], v[104:105], v[52:53] op_sel_hi:[0,1,1]
	v_pk_add_f32 v[50:51], v[82:83], v[50:51] op_sel_hi:[0,1]
	v_pk_add_f32 v[52:53], v[82:83], v[52:53] op_sel_hi:[0,1]
	v_pk_mul_f32 v[50:51], v[58:59], v[50:51]
	v_pk_mul_f32 v[52:53], v[60:61], v[52:53]
	v_cvt_pk_bf16_f32 v50, v50, v51
	v_cvt_pk_bf16_f32 v51, v52, v53
	v_and_b32_e32 v53, 16, v199
	v_and_b32_e32 v52, 0xffff0000, v198
	v_lshlrev_b32_e32 v59, 16, v198
	v_lshlrev_b32_e32 v58, 16, v223
	v_lshlrev_b32_e32 v55, 16, v199
	v_mov_b32_e32 v54, v52
	v_pk_mov_b32 v[52:53], v[58:59], v[52:53] op_sel:[1,0]
	v_pk_mov_b32 v[56:57], v[54:55], v[102:103] op_sel:[1,0]
	v_pk_mul_f32 v[52:53], v[76:77], v[52:53] op_sel_hi:[0,1]
	v_pk_fma_f32 v[52:53], v[72:73], v[58:59], v[52:53] op_sel_hi:[0,1,1]
	v_pk_mul_f32 v[56:57], v[76:77], v[56:57] op_sel_hi:[0,1]
	v_pk_fma_f32 v[52:53], v[74:75], v[54:55], v[52:53] op_sel_hi:[0,1,1]
	v_pk_fma_f32 v[54:55], v[72:73], v[54:55], v[56:57] op_sel_hi:[0,1,1]
	v_pk_fma_f32 v[54:55], v[74:75], v[102:103], v[54:55] op_sel_hi:[0,1,1]
	v_pk_add_f32 v[52:53], v[82:83], v[52:53] op_sel_hi:[0,1]
	v_pk_add_f32 v[54:55], v[82:83], v[54:55] op_sel_hi:[0,1]
	v_pk_mul_f32 v[52:53], v[62:63], v[52:53]
	v_pk_mul_f32 v[54:55], v[64:65], v[54:55]
	v_cvt_pk_bf16_f32 v52, v52, v53
	v_cvt_pk_bf16_f32 v53, v54, v55
	ds_write2_b64 v70, v[50:51], v[52:53] offset0:172 offset1:174
	v_and_b32_e32 v51, 16, v133
	v_and_b32_e32 v50, 0xffff0000, v132
	v_lshlrev_b32_e32 v57, 16, v132
	v_lshlrev_b32_e32 v56, 16, v222
	v_mov_b32_e32 v52, v50
	v_pk_mov_b32 v[50:51], v[56:57], v[50:51] op_sel:[1,0]
	v_lshlrev_b32_e32 v53, 16, v133
	v_pk_mul_f32 v[50:51], v[76:77], v[50:51] op_sel_hi:[0,1]
	v_pk_fma_f32 v[50:51], v[72:73], v[56:57], v[50:51] op_sel_hi:[0,1,1]
	v_pk_fma_f32 v[50:51], v[74:75], v[52:53], v[50:51] op_sel_hi:[0,1,1]
	v_pk_mov_b32 v[54:55], v[52:53], v[100:101] op_sel:[1,0]
	v_pk_add_f32 v[50:51], v[82:83], v[50:51] op_sel_hi:[0,1]
	v_pk_mul_f32 v[34:35], v[34:35], v[50:51]
	v_pk_mul_f32 v[50:51], v[76:77], v[54:55] op_sel_hi:[0,1]
	v_pk_fma_f32 v[50:51], v[72:73], v[52:53], v[50:51] op_sel_hi:[0,1,1]
	v_pk_fma_f32 v[50:51], v[74:75], v[100:101], v[50:51] op_sel_hi:[0,1,1]
	v_pk_add_f32 v[50:51], v[82:83], v[50:51] op_sel_hi:[0,1]
	v_pk_mul_f32 v[36:37], v[36:37], v[50:51]
	v_cvt_pk_bf16_f32 v34, v34, v35
	v_cvt_pk_bf16_f32 v35, v36, v37
	v_and_b32_e32 v37, 16, v131
	v_and_b32_e32 v36, 0xffff0000, v130
	v_lshlrev_b32_e32 v55, 16, v130
	v_lshlrev_b32_e32 v54, 16, v221
	v_mov_b32_e32 v50, v36
	v_pk_mov_b32 v[36:37], v[54:55], v[36:37] op_sel:[1,0]
	v_lshlrev_b32_e32 v51, 16, v131
	v_pk_mul_f32 v[36:37], v[76:77], v[36:37] op_sel_hi:[0,1]
	v_pk_fma_f32 v[36:37], v[72:73], v[54:55], v[36:37] op_sel_hi:[0,1,1]
	v_pk_fma_f32 v[36:37], v[74:75], v[50:51], v[36:37] op_sel_hi:[0,1,1]
	v_pk_mov_b32 v[52:53], v[50:51], v[98:99] op_sel:[1,0]
	v_pk_add_f32 v[36:37], v[82:83], v[36:37] op_sel_hi:[0,1]
	v_pk_mul_f32 v[36:37], v[38:39], v[36:37]
	v_pk_mul_f32 v[38:39], v[76:77], v[52:53] op_sel_hi:[0,1]
	v_pk_fma_f32 v[38:39], v[72:73], v[50:51], v[38:39] op_sel_hi:[0,1,1]
	v_pk_fma_f32 v[38:39], v[74:75], v[98:99], v[38:39] op_sel_hi:[0,1,1]
	v_pk_add_f32 v[38:39], v[82:83], v[38:39] op_sel_hi:[0,1]
	v_pk_mul_f32 v[38:39], v[40:41], v[38:39]
	v_cvt_pk_bf16_f32 v36, v36, v37
	v_cvt_pk_bf16_f32 v37, v38, v39
	v_add_u32_e32 v50, 0x8800, v214
	ds_write2_b64 v50, v[34:35], v[36:37] offset0:168 offset1:170
	v_and_b32_e32 v35, 16, v129
	v_and_b32_e32 v34, 0xffff0000, v128
	v_lshlrev_b32_e32 v41, 16, v128
	v_lshlrev_b32_e32 v40, 16, v220
	v_lshlrev_b32_e32 v37, 16, v129
	v_mov_b32_e32 v36, v34
	v_pk_mov_b32 v[34:35], v[40:41], v[34:35] op_sel:[1,0]
	v_pk_mov_b32 v[38:39], v[36:37], v[96:97] op_sel:[1,0]
	v_pk_mul_f32 v[34:35], v[76:77], v[34:35] op_sel_hi:[0,1]
	v_pk_fma_f32 v[34:35], v[72:73], v[40:41], v[34:35] op_sel_hi:[0,1,1]
	v_pk_mul_f32 v[38:39], v[76:77], v[38:39] op_sel_hi:[0,1]
	v_pk_fma_f32 v[34:35], v[74:75], v[36:37], v[34:35] op_sel_hi:[0,1,1]
	v_pk_fma_f32 v[36:37], v[72:73], v[36:37], v[38:39] op_sel_hi:[0,1,1]
	v_pk_fma_f32 v[36:37], v[74:75], v[96:97], v[36:37] op_sel_hi:[0,1,1]
	v_pk_add_f32 v[34:35], v[82:83], v[34:35] op_sel_hi:[0,1]
	v_pk_add_f32 v[36:37], v[82:83], v[36:37] op_sel_hi:[0,1]
	v_pk_mul_f32 v[34:35], v[42:43], v[34:35]
	v_pk_mul_f32 v[36:37], v[44:45], v[36:37]
	v_cvt_pk_bf16_f32 v34, v34, v35
	v_cvt_pk_bf16_f32 v35, v36, v37
	v_and_b32_e32 v37, 16, v127
	v_and_b32_e32 v36, 0xffff0000, v126
	v_lshlrev_b32_e32 v43, 16, v126
	v_lshlrev_b32_e32 v42, 16, v219
	v_lshlrev_b32_e32 v39, 16, v127
	v_mov_b32_e32 v38, v36
	v_pk_mov_b32 v[36:37], v[42:43], v[36:37] op_sel:[1,0]
	v_pk_mov_b32 v[40:41], v[38:39], v[94:95] op_sel:[1,0]
	v_pk_mul_f32 v[36:37], v[76:77], v[36:37] op_sel_hi:[0,1]
	v_pk_fma_f32 v[36:37], v[72:73], v[42:43], v[36:37] op_sel_hi:[0,1,1]
	v_pk_mul_f32 v[40:41], v[76:77], v[40:41] op_sel_hi:[0,1]
	v_pk_fma_f32 v[36:37], v[74:75], v[38:39], v[36:37] op_sel_hi:[0,1,1]
	v_pk_fma_f32 v[38:39], v[72:73], v[38:39], v[40:41] op_sel_hi:[0,1,1]
	v_pk_fma_f32 v[38:39], v[74:75], v[94:95], v[38:39] op_sel_hi:[0,1,1]
	v_pk_add_f32 v[36:37], v[82:83], v[36:37] op_sel_hi:[0,1]
	v_pk_add_f32 v[38:39], v[82:83], v[38:39] op_sel_hi:[0,1]
	v_pk_mul_f32 v[36:37], v[46:47], v[36:37]
	v_pk_mul_f32 v[38:39], v[48:49], v[38:39]
	v_cvt_pk_bf16_f32 v36, v36, v37
	v_cvt_pk_bf16_f32 v37, v38, v39
	ds_write2_b64 v50, v[34:35], v[36:37] offset0:172 offset1:174
	v_and_b32_e32 v35, 16, v125
	v_and_b32_e32 v34, 0xffff0000, v124
	v_lshlrev_b32_e32 v41, 16, v124
	v_lshlrev_b32_e32 v40, 16, v197
	v_mov_b32_e32 v36, v34
	v_pk_mov_b32 v[34:35], v[40:41], v[34:35] op_sel:[1,0]
	v_lshlrev_b32_e32 v37, 16, v125
	v_pk_mul_f32 v[34:35], v[76:77], v[34:35] op_sel_hi:[0,1]
	v_pk_fma_f32 v[34:35], v[72:73], v[40:41], v[34:35] op_sel_hi:[0,1,1]
	v_pk_fma_f32 v[34:35], v[74:75], v[36:37], v[34:35] op_sel_hi:[0,1,1]
	v_pk_mov_b32 v[38:39], v[36:37], v[92:93] op_sel:[1,0]
	v_pk_add_f32 v[34:35], v[82:83], v[34:35] op_sel_hi:[0,1]
	v_pk_mul_f32 v[18:19], v[18:19], v[34:35]
	v_pk_mul_f32 v[34:35], v[76:77], v[38:39] op_sel_hi:[0,1]
	v_pk_fma_f32 v[34:35], v[72:73], v[36:37], v[34:35] op_sel_hi:[0,1,1]
	v_pk_fma_f32 v[34:35], v[74:75], v[92:93], v[34:35] op_sel_hi:[0,1,1]
	v_pk_add_f32 v[34:35], v[82:83], v[34:35] op_sel_hi:[0,1]
	v_pk_mul_f32 v[20:21], v[20:21], v[34:35]
	v_cvt_pk_bf16_f32 v18, v18, v19
	v_cvt_pk_bf16_f32 v19, v20, v21
	v_and_b32_e32 v21, 16, v123
	v_and_b32_e32 v20, 0xffff0000, v122
	v_lshlrev_b32_e32 v39, 16, v122
	v_lshlrev_b32_e32 v38, 16, v181
	v_mov_b32_e32 v34, v20
	v_pk_mov_b32 v[20:21], v[38:39], v[20:21] op_sel:[1,0]
	v_lshlrev_b32_e32 v35, 16, v123
	v_pk_mul_f32 v[20:21], v[76:77], v[20:21] op_sel_hi:[0,1]
	v_pk_fma_f32 v[20:21], v[72:73], v[38:39], v[20:21] op_sel_hi:[0,1,1]
	v_pk_fma_f32 v[20:21], v[74:75], v[34:35], v[20:21] op_sel_hi:[0,1,1]
	v_pk_mov_b32 v[36:37], v[34:35], v[90:91] op_sel:[1,0]
	v_pk_add_f32 v[20:21], v[82:83], v[20:21] op_sel_hi:[0,1]
	v_pk_mul_f32 v[20:21], v[22:23], v[20:21]
	v_pk_mul_f32 v[22:23], v[76:77], v[36:37] op_sel_hi:[0,1]
	v_pk_fma_f32 v[22:23], v[72:73], v[34:35], v[22:23] op_sel_hi:[0,1,1]
	v_pk_fma_f32 v[22:23], v[74:75], v[90:91], v[22:23] op_sel_hi:[0,1,1]
	v_pk_add_f32 v[22:23], v[82:83], v[22:23] op_sel_hi:[0,1]
	v_pk_mul_f32 v[22:23], v[24:25], v[22:23]
	v_cvt_pk_bf16_f32 v20, v20, v21
	v_cvt_pk_bf16_f32 v21, v22, v23
	v_add_u32_e32 v34, 0x8800, v215
	ds_write2_b64 v34, v[18:19], v[20:21] offset0:168 offset1:170
	v_and_b32_e32 v19, 16, v121
	v_and_b32_e32 v18, 0xffff0000, v120
	v_lshlrev_b32_e32 v25, 16, v120
	v_lshlrev_b32_e32 v24, 16, v177
	v_lshlrev_b32_e32 v21, 16, v121
	v_mov_b32_e32 v20, v18
	v_pk_mov_b32 v[18:19], v[24:25], v[18:19] op_sel:[1,0]
	v_pk_mov_b32 v[22:23], v[20:21], v[88:89] op_sel:[1,0]
	v_pk_mul_f32 v[18:19], v[76:77], v[18:19] op_sel_hi:[0,1]
	v_pk_fma_f32 v[18:19], v[72:73], v[24:25], v[18:19] op_sel_hi:[0,1,1]
	v_pk_mul_f32 v[22:23], v[76:77], v[22:23] op_sel_hi:[0,1]
	v_pk_fma_f32 v[18:19], v[74:75], v[20:21], v[18:19] op_sel_hi:[0,1,1]
	v_pk_fma_f32 v[20:21], v[72:73], v[20:21], v[22:23] op_sel_hi:[0,1,1]
	v_pk_fma_f32 v[20:21], v[74:75], v[88:89], v[20:21] op_sel_hi:[0,1,1]
	v_pk_add_f32 v[18:19], v[82:83], v[18:19] op_sel_hi:[0,1]
	v_pk_add_f32 v[20:21], v[82:83], v[20:21] op_sel_hi:[0,1]
	v_pk_mul_f32 v[18:19], v[26:27], v[18:19]
	v_pk_mul_f32 v[20:21], v[28:29], v[20:21]
	v_cvt_pk_bf16_f32 v18, v18, v19
	v_cvt_pk_bf16_f32 v19, v20, v21
	v_and_b32_e32 v21, 16, v119
	v_and_b32_e32 v20, 0xffff0000, v118
	v_lshlrev_b32_e32 v27, 16, v118
	v_lshlrev_b32_e32 v26, 16, v175
	v_lshlrev_b32_e32 v23, 16, v119
	v_mov_b32_e32 v22, v20
	v_pk_mov_b32 v[20:21], v[26:27], v[20:21] op_sel:[1,0]
	v_pk_mov_b32 v[24:25], v[22:23], v[86:87] op_sel:[1,0]
	v_pk_mul_f32 v[20:21], v[76:77], v[20:21] op_sel_hi:[0,1]
	v_pk_fma_f32 v[20:21], v[72:73], v[26:27], v[20:21] op_sel_hi:[0,1,1]
	v_pk_mul_f32 v[24:25], v[76:77], v[24:25] op_sel_hi:[0,1]
	v_pk_fma_f32 v[20:21], v[74:75], v[22:23], v[20:21] op_sel_hi:[0,1,1]
	v_pk_fma_f32 v[22:23], v[72:73], v[22:23], v[24:25] op_sel_hi:[0,1,1]
	v_pk_fma_f32 v[22:23], v[74:75], v[86:87], v[22:23] op_sel_hi:[0,1,1]
	v_pk_add_f32 v[20:21], v[82:83], v[20:21] op_sel_hi:[0,1]
	v_pk_add_f32 v[22:23], v[82:83], v[22:23] op_sel_hi:[0,1]
	v_pk_mul_f32 v[20:21], v[30:31], v[20:21]
	v_pk_mul_f32 v[22:23], v[32:33], v[22:23]
	v_cvt_pk_bf16_f32 v20, v20, v21
	v_cvt_pk_bf16_f32 v21, v22, v23
	ds_write2_b64 v34, v[18:19], v[20:21] offset0:172 offset1:174
	v_and_b32_e32 v19, 16, v117
	v_and_b32_e32 v18, 0xffff0000, v116
	v_lshlrev_b32_e32 v25, 16, v116
	v_lshlrev_b32_e32 v24, 16, v173
	v_mov_b32_e32 v20, v18
	v_pk_mov_b32 v[18:19], v[24:25], v[18:19] op_sel:[1,0]
	v_lshlrev_b32_e32 v21, 16, v117
	v_pk_mul_f32 v[18:19], v[76:77], v[18:19] op_sel_hi:[0,1]
	v_pk_fma_f32 v[18:19], v[72:73], v[24:25], v[18:19] op_sel_hi:[0,1,1]
	v_pk_fma_f32 v[18:19], v[74:75], v[20:21], v[18:19] op_sel_hi:[0,1,1]
	v_pk_mov_b32 v[22:23], v[20:21], v[84:85] op_sel:[1,0]
	v_pk_add_f32 v[18:19], v[82:83], v[18:19] op_sel_hi:[0,1]
	v_pk_mul_f32 v[2:3], v[2:3], v[18:19]
	v_pk_mul_f32 v[18:19], v[76:77], v[22:23] op_sel_hi:[0,1]
	v_pk_fma_f32 v[18:19], v[72:73], v[20:21], v[18:19] op_sel_hi:[0,1,1]
	v_pk_fma_f32 v[18:19], v[74:75], v[84:85], v[18:19] op_sel_hi:[0,1,1]
	v_pk_add_f32 v[18:19], v[82:83], v[18:19] op_sel_hi:[0,1]
	v_pk_mul_f32 v[4:5], v[4:5], v[18:19]
	v_cvt_pk_bf16_f32 v2, v2, v3
	v_cvt_pk_bf16_f32 v3, v4, v5
	v_and_b32_e32 v5, 16, v115
	v_and_b32_e32 v4, 0xffff0000, v114
	v_lshlrev_b32_e32 v23, 16, v114
	v_lshlrev_b32_e32 v22, 16, v171
	v_mov_b32_e32 v18, v4
	v_pk_mov_b32 v[4:5], v[22:23], v[4:5] op_sel:[1,0]
	v_lshlrev_b32_e32 v19, 16, v115
	v_pk_mul_f32 v[4:5], v[76:77], v[4:5] op_sel_hi:[0,1]
	v_pk_fma_f32 v[4:5], v[72:73], v[22:23], v[4:5] op_sel_hi:[0,1,1]
	v_pk_fma_f32 v[4:5], v[74:75], v[18:19], v[4:5] op_sel_hi:[0,1,1]
	v_pk_mov_b32 v[20:21], v[18:19], v[80:81] op_sel:[1,0]
	v_pk_add_f32 v[4:5], v[82:83], v[4:5] op_sel_hi:[0,1]
	v_pk_mul_f32 v[4:5], v[6:7], v[4:5]
	v_pk_mul_f32 v[6:7], v[76:77], v[20:21] op_sel_hi:[0,1]
	v_pk_fma_f32 v[6:7], v[72:73], v[18:19], v[6:7] op_sel_hi:[0,1,1]
	v_pk_fma_f32 v[6:7], v[74:75], v[80:81], v[6:7] op_sel_hi:[0,1,1]
	v_pk_add_f32 v[6:7], v[82:83], v[6:7] op_sel_hi:[0,1]
	v_pk_mul_f32 v[6:7], v[8:9], v[6:7]
	v_cvt_pk_bf16_f32 v4, v4, v5
	v_cvt_pk_bf16_f32 v5, v6, v7
	v_add_u32_e32 v18, 0x8800, v216
	ds_write2_b64 v18, v[2:3], v[4:5] offset0:168 offset1:170
	v_and_b32_e32 v3, 16, v113
	v_and_b32_e32 v2, 0xffff0000, v112
	v_lshlrev_b32_e32 v9, 16, v112
	v_lshlrev_b32_e32 v8, 16, v169
	v_lshlrev_b32_e32 v5, 16, v113
	v_mov_b32_e32 v4, v2
	v_pk_mov_b32 v[2:3], v[8:9], v[2:3] op_sel:[1,0]
	v_pk_mov_b32 v[6:7], v[4:5], v[78:79] op_sel:[1,0]
	v_pk_mul_f32 v[2:3], v[76:77], v[2:3] op_sel_hi:[0,1]
	v_pk_fma_f32 v[2:3], v[72:73], v[8:9], v[2:3] op_sel_hi:[0,1,1]
	v_pk_mul_f32 v[6:7], v[76:77], v[6:7] op_sel_hi:[0,1]
	v_pk_fma_f32 v[2:3], v[74:75], v[4:5], v[2:3] op_sel_hi:[0,1,1]
	v_pk_fma_f32 v[4:5], v[72:73], v[4:5], v[6:7] op_sel_hi:[0,1,1]
	v_pk_fma_f32 v[4:5], v[74:75], v[78:79], v[4:5] op_sel_hi:[0,1,1]
	v_pk_add_f32 v[2:3], v[82:83], v[2:3] op_sel_hi:[0,1]
	v_pk_add_f32 v[4:5], v[82:83], v[4:5] op_sel_hi:[0,1]
	v_pk_mul_f32 v[2:3], v[10:11], v[2:3]
	v_pk_mul_f32 v[4:5], v[12:13], v[4:5]
	v_cvt_pk_bf16_f32 v2, v2, v3
	v_cvt_pk_bf16_f32 v3, v4, v5
	v_and_b32_e32 v5, 16, v111
	v_and_b32_e32 v4, 0xffff0000, v110
	v_lshlrev_b32_e32 v11, 16, v110
	v_lshlrev_b32_e32 v10, 16, v136
	v_and_b32_e32 v70, 0xffff0000, v111
	v_lshlrev_b32_e32 v7, 16, v111
	v_mov_b32_e32 v6, v4
	v_pk_mov_b32 v[4:5], v[10:11], v[4:5] op_sel:[1,0]
	v_pk_mov_b32 v[8:9], v[6:7], v[70:71] op_sel:[1,0]
	v_pk_mul_f32 v[4:5], v[76:77], v[4:5] op_sel_hi:[0,1]
	v_pk_fma_f32 v[4:5], v[72:73], v[10:11], v[4:5] op_sel_hi:[0,1,1]
	v_pk_mul_f32 v[8:9], v[76:77], v[8:9] op_sel_hi:[0,1]
	v_pk_fma_f32 v[4:5], v[74:75], v[6:7], v[4:5] op_sel_hi:[0,1,1]
	v_pk_fma_f32 v[6:7], v[72:73], v[6:7], v[8:9] op_sel_hi:[0,1,1]
	v_pk_fma_f32 v[6:7], v[74:75], v[70:71], v[6:7] op_sel_hi:[0,1,1]
	v_pk_add_f32 v[4:5], v[82:83], v[4:5] op_sel_hi:[0,1]
	v_pk_add_f32 v[6:7], v[82:83], v[6:7] op_sel_hi:[0,1]
	v_pk_mul_f32 v[4:5], v[14:15], v[4:5]
	v_pk_mul_f32 v[6:7], v[16:17], v[6:7]
	v_cvt_pk_bf16_f32 v4, v4, v5
	v_cvt_pk_bf16_f32 v5, v6, v7
	ds_write2_b64 v18, v[2:3], v[4:5] offset0:172 offset1:174

.LBB0_706:
	v_readfirstlane_b32 s101, v0
	v_and_b32_e32 v253, 63, v0
	v_lshlrev_b32_e32 v253, 4, v253
	s_lshr_b32 s101, s101, 6
	s_add_i32 s98, s90, 0x400
	s_lshl_b32 s100, s101, 10
	s_lshl_b32 s98, s98, 12
	s_add_u32 s98, s98, s100
	s_add_u32 s98, s4, s98
	s_addc_u32 s99, s5, 0
	s_add_i32 s100, s100, 0xc0
	s_mov_b32 m0, s100
	s_nop 0
	global_load_lds_dwordx4 v253, s[98:99]
	s_addk_i32 s100, 0x1190
	s_mov_b32 m0, s100
	s_add_u32 s98, s98, 0x600000
	s_addc_u32 s99, s99, 0
	global_load_lds_dwordx4 v253, s[98:99]
	s_addk_i32 s100, 0x1190
	s_mov_b32 m0, s100
	s_add_u32 s98, s98, 0x600000
	s_addc_u32 s99, s99, 0
	global_load_lds_dwordx4 v253, s[98:99]
	s_addk_i32 s100, 0x1190
	s_mov_b32 m0, s100
	s_add_u32 s98, s98, 0x600000
	s_addc_u32 s99, s99, 0
	global_load_lds_dwordx4 v253, s[98:99]
	s_addk_i32 s100, 0x1190
	s_mov_b32 m0, s100
	s_add_u32 s98, s98, 0x600000
	s_addc_u32 s99, s99, 0
	global_load_lds_dwordx4 v253, s[98:99]
	s_addk_i32 s100, 0x1190
	s_mov_b32 m0, s100
	s_add_u32 s98, s98, 0x600000
	s_addc_u32 s99, s99, 0
	global_load_lds_dwordx4 v253, s[98:99]
	s_addk_i32 s100, 0x1190
	s_mov_b32 m0, s100
	s_add_u32 s98, s98, 0x600000
	s_addc_u32 s99, s99, 0
	global_load_lds_dwordx4 v253, s[98:99]
	s_addk_i32 s100, 0x1190
	s_mov_b32 m0, s100
	s_add_u32 s98, s98, 0x600000
	s_addc_u32 s99, s99, 0
	global_load_lds_dwordx4 v253, s[98:99]
	global_load_dword v250, v207, s[92:93]
	global_load_dword v253, v212, s[92:93] offset:2048
	global_load_dword v254, v217, s[92:93]
	global_load_dword v255, v207, s[94:95]
	s_waitcnt vmcnt(14)
	s_nop 2
	ds_read_b128 v[2:5], v218 offset:4032
	s_waitcnt vmcnt(12)
	ds_read_b128 v[6:9], v218 offset:4064
	s_waitcnt vmcnt(10)
	ds_read_b128 v[10:13], v1 offset:40192
	s_waitcnt vmcnt(8)
	ds_read_b128 v[14:17], v1 offset:40224
	s_waitcnt vmcnt(6)
	ds_read_b128 v[18:21], v218 offset:3968
	s_waitcnt vmcnt(4)
	ds_read_b128 v[22:25], v218 offset:4000
	s_mov_b32 s10, 0
	s_waitcnt vmcnt(1) lgkmcnt(3)
	v_mfma_f32_32x32x16_bf16 v[50:65], v[2:5], v[10:13], 0
	ds_read_b128 v[2:5], v1 offset:40128
	ds_read_b128 v[10:13], v1 offset:40160
	s_waitcnt lgkmcnt(4)
	v_mfma_f32_32x32x16_bf16 v[50:65], v[6:9], v[14:17], v[50:65]
	s_waitcnt lgkmcnt(1)
	v_mfma_f32_32x32x16_bf16 v[50:65], v[18:21], v[2:5], v[50:65]
	ds_read_b128 v[6:9], v218 offset:3904
	ds_read_b128 v[14:17], v218 offset:3936
	ds_read_b128 v[2:5], v1 offset:40064
	ds_read_b128 v[18:21], v1 offset:40096
	s_waitcnt lgkmcnt(4)
	v_mfma_f32_32x32x16_bf16 v[50:65], v[22:25], v[10:13], v[50:65]
	s_waitcnt lgkmcnt(1)
	v_mfma_f32_32x32x16_bf16 v[50:65], v[6:9], v[2:5], v[50:65]
	ds_read_b128 v[10:13], v218 offset:3840
	ds_read_b128 v[22:25], v218 offset:3872
	ds_read_b128 v[2:5], v1 offset:40000
	ds_read_b128 v[6:9], v1 offset:40032
	s_waitcnt lgkmcnt(4)
	v_mfma_f32_32x32x16_bf16 v[50:65], v[14:17], v[18:21], v[50:65]
	s_waitcnt lgkmcnt(1)
	v_mfma_f32_32x32x16_bf16 v[50:65], v[10:13], v[2:5], v[50:65]
	ds_read_b128 v[14:17], v218 offset:3776
	ds_read_b128 v[18:21], v218 offset:3808
	ds_read_b128 v[2:5], v1 offset:39936
	ds_read_b128 v[10:13], v1 offset:39968
	ds_read_b128 v[26:29], v1 offset:40192
	s_waitcnt vmcnt(0)
	ds_read_b128 v[30:33], v1 offset:40224
	s_waitcnt lgkmcnt(6)
	v_mfma_f32_32x32x16_bf16 v[50:65], v[22:25], v[6:9], v[50:65]
	s_waitcnt lgkmcnt(3)
	v_mfma_f32_32x32x16_bf16 v[50:65], v[14:17], v[2:5], v[50:65]
	ds_read_b128 v[2:5], v218 offset:3712
	ds_read_b128 v[6:9], v218 offset:3744
	s_waitcnt lgkmcnt(3)
	v_mfma_f32_32x32x16_bf16 v[34:49], v[14:17], v[26:29], 0
	ds_read_b128 v[14:17], v1 offset:39872
	ds_read_b128 v[22:25], v1 offset:39904
	ds_read_b128 v[26:29], v1 offset:40128
	ds_read_b128 v[66:69], v1 offset:40160
	v_mfma_f32_32x32x16_bf16 v[50:65], v[18:21], v[10:13], v[50:65]
	s_waitcnt lgkmcnt(6)
	v_mfma_f32_32x32x16_bf16 v[34:49], v[18:21], v[30:33], v[34:49]
	s_waitcnt lgkmcnt(3)
	v_mfma_f32_32x32x16_bf16 v[50:65], v[2:5], v[14:17], v[50:65]
	ds_read_b128 v[10:13], v218 offset:3648
	ds_read_b128 v[14:17], v218 offset:3680
	s_waitcnt lgkmcnt(3)
	v_mfma_f32_32x32x16_bf16 v[34:49], v[2:5], v[26:29], v[34:49]
	ds_read_b128 v[2:5], v1 offset:39808
	ds_read_b128 v[18:21], v1 offset:39840
	ds_read_b128 v[26:29], v1 offset:40064
	ds_read_b128 v[30:33], v1 offset:40096
	v_mfma_f32_32x32x16_bf16 v[50:65], v[6:9], v[22:25], v[50:65]
	s_waitcnt lgkmcnt(6)
	v_mfma_f32_32x32x16_bf16 v[34:49], v[6:9], v[66:69], v[34:49]
	s_waitcnt lgkmcnt(3)
	v_mfma_f32_32x32x16_bf16 v[50:65], v[10:13], v[2:5], v[50:65]
	ds_read_b128 v[2:5], v218 offset:3584
	ds_read_b128 v[6:9], v218 offset:3616
	s_waitcnt lgkmcnt(3)
	v_mfma_f32_32x32x16_bf16 v[34:49], v[10:13], v[26:29], v[34:49]
	ds_read_b128 v[10:13], v1 offset:39744
	ds_read_b128 v[22:25], v1 offset:39776
	ds_read_b128 v[26:29], v1 offset:40000
	ds_read_b128 v[66:69], v1 offset:40032
	v_mfma_f32_32x32x16_bf16 v[50:65], v[14:17], v[18:21], v[50:65]
	s_waitcnt lgkmcnt(6)
	v_mfma_f32_32x32x16_bf16 v[34:49], v[14:17], v[30:33], v[34:49]
	s_waitcnt lgkmcnt(3)
	v_mfma_f32_32x32x16_bf16 v[50:65], v[2:5], v[10:13], v[50:65]
	ds_read_b128 v[10:13], v218 offset:3520
	ds_read_b128 v[14:17], v218 offset:3552
	s_waitcnt lgkmcnt(3)
	v_mfma_f32_32x32x16_bf16 v[34:49], v[2:5], v[26:29], v[34:49]
	ds_read_b128 v[2:5], v1 offset:39680
	ds_read_b128 v[70:73], v1 offset:39712
	ds_read_b128 v[18:21], v1 offset:39936
	ds_read_b128 v[74:77], v1 offset:39968
	v_mfma_f32_32x32x16_bf16 v[50:65], v[6:9], v[22:25], v[50:65]
	ds_read_b128 v[26:29], v1 offset:40192
	ds_read_b128 v[78:81], v1 offset:40224
	s_waitcnt lgkmcnt(8)
	v_mfma_f32_32x32x16_bf16 v[34:49], v[6:9], v[66:69], v[34:49]
	s_waitcnt lgkmcnt(5)
	v_mfma_f32_32x32x16_bf16 v[50:65], v[10:13], v[2:5], v[50:65]
	ds_read_b128 v[2:5], v218 offset:3456
	ds_read_b128 v[6:9], v218 offset:3488
	s_waitcnt lgkmcnt(5)
	v_mfma_f32_32x32x16_bf16 v[34:49], v[10:13], v[18:21], v[34:49]
	s_waitcnt lgkmcnt(3)
	v_mfma_f32_32x32x16_bf16 v[18:33], v[10:13], v[26:29], 0
	ds_read_b128 v[66:69], v1 offset:39616
	ds_read_b128 v[82:85], v1 offset:39648
	ds_read_b128 v[10:13], v1 offset:39872
	ds_read_b128 v[86:89], v1 offset:39904
	v_mfma_f32_32x32x16_bf16 v[50:65], v[14:17], v[70:73], v[50:65]
	ds_read_b128 v[90:93], v1 offset:40128
	ds_read_b128 v[94:97], v1 offset:40160
	v_mfma_f32_32x32x16_bf16 v[34:49], v[14:17], v[74:77], v[34:49]
	s_waitcnt lgkmcnt(8)
	v_mfma_f32_32x32x16_bf16 v[18:33], v[14:17], v[78:81], v[18:33]
	s_waitcnt lgkmcnt(5)
	v_mfma_f32_32x32x16_bf16 v[50:65], v[2:5], v[66:69], v[50:65]
	ds_read_b128 v[14:17], v218 offset:3392
	ds_read_b128 v[66:69], v218 offset:3424
	s_waitcnt lgkmcnt(5)
	v_mfma_f32_32x32x16_bf16 v[34:49], v[2:5], v[10:13], v[34:49]
	s_waitcnt lgkmcnt(3)
	v_mfma_f32_32x32x16_bf16 v[18:33], v[2:5], v[90:93], v[18:33]
	ds_read_b128 v[10:13], v1 offset:39552
	ds_read_b128 v[70:73], v1 offset:39584
	ds_read_b128 v[2:5], v1 offset:39808
	ds_read_b128 v[74:77], v1 offset:39840
	v_mfma_f32_32x32x16_bf16 v[50:65], v[6:9], v[82:85], v[50:65]
	ds_read_b128 v[78:81], v1 offset:40064
	ds_read_b128 v[90:93], v1 offset:40096
	v_mfma_f32_32x32x16_bf16 v[34:49], v[6:9], v[86:89], v[34:49]
	s_waitcnt lgkmcnt(8)
	v_mfma_f32_32x32x16_bf16 v[18:33], v[6:9], v[94:97], v[18:33]
	s_waitcnt lgkmcnt(5)
	v_mfma_f32_32x32x16_bf16 v[50:65], v[14:17], v[10:13], v[50:65]
	ds_read_b128 v[6:9], v218 offset:3328
	ds_read_b128 v[10:13], v218 offset:3360
	s_waitcnt lgkmcnt(5)
	v_mfma_f32_32x32x16_bf16 v[34:49], v[14:17], v[2:5], v[34:49]
	s_waitcnt lgkmcnt(3)
	v_mfma_f32_32x32x16_bf16 v[18:33], v[14:17], v[78:81], v[18:33]
	ds_read_b128 v[2:5], v1 offset:39488
	ds_read_b128 v[86:89], v1 offset:39520
	ds_read_b128 v[14:17], v1 offset:39744
	ds_read_b128 v[106:109], v1 offset:39776
	v_mfma_f32_32x32x16_bf16 v[50:65], v[66:69], v[70:73], v[50:65]
	ds_read_b128 v[78:81], v1 offset:40000
	ds_read_b128 v[110:113], v1 offset:40032
	v_mfma_f32_32x32x16_bf16 v[34:49], v[66:69], v[74:77], v[34:49]
	s_waitcnt lgkmcnt(8)
	v_mfma_f32_32x32x16_bf16 v[18:33], v[66:69], v[90:93], v[18:33]
	s_waitcnt lgkmcnt(5)
	v_mfma_f32_32x32x16_bf16 v[50:65], v[6:9], v[2:5], v[50:65]
	ds_read_b128 v[70:73], v218 offset:3264
	ds_read_b128 v[66:69], v218 offset:3296
	s_waitcnt lgkmcnt(5)
	v_mfma_f32_32x32x16_bf16 v[34:49], v[6:9], v[14:17], v[34:49]
	s_waitcnt lgkmcnt(3)
	v_mfma_f32_32x32x16_bf16 v[18:33], v[6:9], v[78:81], v[18:33]
	ds_read_b128 v[102:105], v1 offset:39424
	ds_read_b128 v[74:77], v1 offset:39456
	ds_read_b128 v[90:93], v1 offset:39680
	ds_read_b128 v[78:81], v1 offset:39712
	v_mfma_f32_32x32x16_bf16 v[50:65], v[10:13], v[86:89], v[50:65]
	ds_read_b128 v[94:97], v1 offset:39936
	ds_read_b128 v[82:85], v1 offset:39968
	v_mfma_f32_32x32x16_bf16 v[34:49], v[10:13], v[106:109], v[34:49]
	ds_read_b128 v[98:101], v1 offset:40192
	ds_read_b128 v[86:89], v1 offset:40224
	s_waitcnt lgkmcnt(10)
	v_mfma_f32_32x32x16_bf16 v[18:33], v[10:13], v[110:113], v[18:33]
	v_mov_b32_e32 v2, 0
	v_mov_b32_e32 v3, v2
	v_mov_b32_e32 v4, v2
	v_mov_b32_e32 v5, v2
	v_mov_b32_e32 v6, v2
	v_mov_b32_e32 v7, v2
	v_mov_b32_e32 v8, v2
	v_mov_b32_e32 v9, v2
	v_mov_b32_e32 v10, v2
	v_mov_b32_e32 v11, v2
	v_mov_b32_e32 v12, v2
	v_mov_b32_e32 v13, v2
	v_mov_b32_e32 v14, v2
	v_mov_b32_e32 v15, v2
	v_mov_b32_e32 v16, v2
	v_mov_b32_e32 v17, v2
.LBB0_707:
	s_waitcnt lgkmcnt(7)
	v_mfma_f32_32x32x16_bf16 v[50:65], v[70:73], v[102:105], v[50:65]
	v_add_u32_e32 v102, s10, v179
	v_add_u32_e32 v103, 0x12580, v102
	v_add_u32_e32 v104, 0x125a0, v102
	ds_read_b128 v[106:109], v103
	ds_read_b128 v[110:113], v104
	v_add_u32_e32 v136, s10, v159
	s_waitcnt lgkmcnt(7)
	v_mfma_f32_32x32x16_bf16 v[34:49], v[70:73], v[90:93], v[34:49]
	s_waitcnt lgkmcnt(5)
	v_mfma_f32_32x32x16_bf16 v[18:33], v[70:73], v[94:97], v[18:33]
	ds_read_b128 v[90:93], v136
	ds_read_b128 v[114:117], v136 offset:32
	s_waitcnt lgkmcnt(5)
	v_mfma_f32_32x32x16_bf16 v[2:17], v[70:73], v[98:101], v[2:17]
	ds_read_b128 v[94:97], v136 offset:256
	ds_read_b128 v[118:121], v136 offset:288
	v_mfma_f32_32x32x16_bf16 v[50:65], v[66:69], v[74:77], v[50:65]
	ds_read_b128 v[98:101], v136 offset:512
	ds_read_b128 v[122:125], v136 offset:544
	v_mfma_f32_32x32x16_bf16 v[34:49], v[66:69], v[78:81], v[34:49]
	ds_read_b128 v[126:129], v136 offset:768
	ds_read_b128 v[130:133], v136 offset:800
	v_mfma_f32_32x32x16_bf16 v[18:33], v[66:69], v[82:85], v[18:33]
	s_waitcnt lgkmcnt(10)
	v_mfma_f32_32x32x16_bf16 v[2:17], v[66:69], v[86:89], v[2:17]
	s_waitcnt lgkmcnt(7)
	v_mfma_f32_32x32x16_bf16 v[50:65], v[106:109], v[90:93], v[50:65]
	v_add_u32_e32 v66, 0x12540, v102
	v_add_u32_e32 v67, 0x12560, v102
	ds_read_b128 v[70:73], v66
	ds_read_b128 v[66:69], v67
	s_waitcnt lgkmcnt(7)
	v_mfma_f32_32x32x16_bf16 v[34:49], v[106:109], v[94:97], v[34:49]
	s_waitcnt lgkmcnt(5)
	v_mfma_f32_32x32x16_bf16 v[18:33], v[106:109], v[98:101], v[18:33]
	v_subrev_u32_e32 v74, 64, v136
	ds_read_b128 v[102:105], v74
	ds_read_b128 v[74:77], v74 offset:32
	s_waitcnt lgkmcnt(5)
	v_mfma_f32_32x32x16_bf16 v[2:17], v[106:109], v[126:129], v[2:17]
	ds_read_b128 v[90:93], v136 offset:192
	ds_read_b128 v[78:81], v136 offset:224
	v_mfma_f32_32x32x16_bf16 v[50:65], v[110:113], v[114:117], v[50:65]
	ds_read_b128 v[94:97], v136 offset:448
	ds_read_b128 v[82:85], v136 offset:480
	v_mfma_f32_32x32x16_bf16 v[34:49], v[110:113], v[118:121], v[34:49]
	ds_read_b128 v[98:101], v136 offset:704
	ds_read_b128 v[86:89], v136 offset:736
	v_mfma_f32_32x32x16_bf16 v[18:33], v[110:113], v[122:125], v[18:33]
	s_waitcnt lgkmcnt(10)
	v_mfma_f32_32x32x16_bf16 v[2:17], v[110:113], v[130:133], v[2:17]
	s_addk_i32 s10, 0xff80
	s_cmpk_eq_i32 s10, 0xf280
	s_cbranch_scc0 .LBB0_707
	v_add_u32_e32 v231, s10, v179
	s_add_i32 s10, s90, 0x400
	s_ashr_i32 s11, s10, 31
	v_lshl_add_u64 v[106:107], v[160:161], 0, s[10:11]
	v_lshlrev_b64 v[106:107], 12, v[106:107]
	v_lshl_add_u64 v[232:233], s[4:5], 0, v[106:107]
	v_lshlrev_b32_e32 v136, 1, v152
	v_lshlrev_b32_e32 v106, 1, v154
	v_mov_b32_e32 v107, v137
	v_lshl_add_u64 v[234:235], v[232:233], 0, v[136:137]
	v_lshl_add_u64 v[106:107], v[232:233], 0, v[106:107]
	s_waitcnt vmcnt(0)
	v_bfe_u32 v136, v0, 2, 3
	v_mul_u32_u24_e32 v136, 0x1190, v136
	v_lshl_add_u32 v136, v152, 1, v136
	ds_read_b64 v[200:201], v136 offset:192
	global_load_ushort v202, v[106:107], off offset:-2
	ds_read_u16 v203, v136 offset:200
	ds_read_b64 v[198:199], v136 offset:208
	ds_read_u16 v195, v136 offset:206
	ds_read_u16 v204, v136 offset:216
	ds_read_b64 v[132:133], v136 offset:224
	ds_read_u16 v193, v136 offset:222
	ds_read_u16 v205, v136 offset:232
	ds_read_b64 v[130:131], v136 offset:240
	ds_read_u16 v191, v136 offset:238
	ds_read_u16 v219, v136 offset:248
	ds_read_b64 v[128:129], v136 offset:448
	ds_read_u16 v189, v136 offset:446
	ds_read_u16 v220, v136 offset:456
	ds_read_b64 v[126:127], v136 offset:464
	ds_read_u16 v187, v136 offset:462
	ds_read_u16 v221, v136 offset:472
	ds_read_b64 v[124:125], v136 offset:480
	ds_read_u16 v185, v136 offset:478
	ds_read_u16 v222, v136 offset:488
	ds_read_b64 v[122:123], v136 offset:496
	ds_read_u16 v183, v136 offset:494
	ds_read_u16 v223, v136 offset:504
	ds_read_b64 v[120:121], v136 offset:704
	ds_read_u16 v181, v136 offset:702
	ds_read_u16 v224, v136 offset:712
	ds_read_b64 v[118:119], v136 offset:720
	ds_read_u16 v177, v136 offset:718
	ds_read_u16 v225, v136 offset:728
	ds_read_b64 v[116:117], v136 offset:736
	ds_read_u16 v175, v136 offset:734
	ds_read_u16 v226, v136 offset:744
	ds_read_b64 v[114:115], v136 offset:752
	ds_read_u16 v173, v136 offset:750
	ds_read_u16 v227, v136 offset:760
	ds_read_b64 v[112:113], v136 offset:960
	ds_read_u16 v171, v136 offset:958
	ds_read_u16 v228, v136 offset:968
	ds_read_b64 v[110:111], v136 offset:976
	ds_read_u16 v169, v136 offset:974
	ds_read_u16 v229, v136 offset:984
	ds_read_b64 v[108:109], v136 offset:992
	ds_read_u16 v167, v136 offset:990
	ds_read_u16 v230, v136 offset:1000
	ds_read_b64 v[106:107], v136 offset:1008
	ds_read_u16 v165, v136 offset:1006
	v_mov_b32_e32 v197, v137
	v_lshl_add_u64 v[232:233], v[232:233], 0, v[196:197]
	global_load_ushort v197, v[232:233], off offset:8
	v_lshlrev_b32_e32 v136, 1, v152
	s_waitcnt lgkmcnt(7)
	v_mfma_f32_32x32x16_bf16 v[50:65], v[70:73], v[102:105], v[50:65]
	v_add_u32_e32 v236, 0x12580, v231
	ds_read_b128 v[232:235], v236
	v_add_u32_e32 v236, 0x125a0, v231
	ds_read_b128 v[242:245], v236
	s_waitcnt lgkmcnt(7)
	v_mfma_f32_32x32x16_bf16 v[34:49], v[70:73], v[90:93], v[34:49]
	s_waitcnt lgkmcnt(5)
	v_mfma_f32_32x32x16_bf16 v[18:33], v[70:73], v[94:97], v[18:33]
	s_waitcnt lgkmcnt(3)
	v_mfma_f32_32x32x16_bf16 v[2:17], v[70:73], v[98:101], v[2:17]
	ds_read_b128 v[90:93], v1 offset:36160
	ds_read_b128 v[94:97], v1 offset:36192
	v_mfma_f32_32x32x16_bf16 v[50:65], v[66:69], v[74:77], v[50:65]
	ds_read_b128 v[70:73], v1 offset:36416
	ds_read_b128 v[98:101], v1 offset:36448
	v_mfma_f32_32x32x16_bf16 v[34:49], v[66:69], v[78:81], v[34:49]
	ds_read_b128 v[74:77], v1 offset:36672
	ds_read_b128 v[102:105], v1 offset:36704
	v_mfma_f32_32x32x16_bf16 v[18:33], v[66:69], v[82:85], v[18:33]
	s_waitcnt lgkmcnt(8)
	v_mfma_f32_32x32x16_bf16 v[2:17], v[66:69], v[86:89], v[2:17]
	s_waitcnt lgkmcnt(5)
	v_mfma_f32_32x32x16_bf16 v[34:49], v[232:235], v[90:93], v[34:49]
	v_add_u32_e32 v66, 0x12540, v231
	v_add_u32_e32 v78, 0x12560, v231
	ds_read_b128 v[66:69], v66
	ds_read_b128 v[78:81], v78
	s_waitcnt lgkmcnt(5)
	v_mfma_f32_32x32x16_bf16 v[18:33], v[232:235], v[70:73], v[18:33]
	s_waitcnt lgkmcnt(3)
	v_mfma_f32_32x32x16_bf16 v[2:17], v[232:235], v[74:77], v[2:17]
	ds_read_b128 v[70:73], v1 offset:36096
	ds_read_b128 v[82:85], v1 offset:36128
	ds_read_b128 v[74:77], v1 offset:36352
	ds_read_b128 v[86:89], v1 offset:36384
	v_mfma_f32_32x32x16_bf16 v[34:49], v[242:245], v[94:97], v[34:49]
	ds_read_b128 v[90:93], v1 offset:36608
	ds_read_b128 v[232:235], v1 offset:36640
	v_mfma_f32_32x32x16_bf16 v[18:33], v[242:245], v[98:101], v[18:33]
	s_waitcnt lgkmcnt(8)
	v_mfma_f32_32x32x16_bf16 v[2:17], v[242:245], v[102:105], v[2:17]
	s_waitcnt lgkmcnt(5)
	v_mfma_f32_32x32x16_bf16 v[34:49], v[66:69], v[70:73], v[34:49]
	v_add_u32_e32 v94, 0x12500, v231
	v_add_u32_e32 v98, 0x12520, v231
	ds_read_b128 v[94:97], v94
	ds_read_b128 v[98:101], v98
	s_waitcnt lgkmcnt(5)
	v_mfma_f32_32x32x16_bf16 v[18:33], v[66:69], v[74:77], v[18:33]
	s_waitcnt lgkmcnt(3)
	v_mfma_f32_32x32x16_bf16 v[2:17], v[66:69], v[90:93], v[2:17]
	ds_read_b128 v[70:73], v1 offset:36032
	ds_read_b128 v[74:77], v1 offset:36064
	ds_read_b128 v[66:69], v1 offset:36288
	ds_read_b128 v[90:93], v1 offset:36320
	v_mfma_f32_32x32x16_bf16 v[34:49], v[78:81], v[82:85], v[34:49]
	ds_read_b128 v[102:105], v1 offset:36544
	ds_read_b128 v[242:245], v1 offset:36576
	v_mfma_f32_32x32x16_bf16 v[18:33], v[78:81], v[86:89], v[18:33]
	s_waitcnt lgkmcnt(8)
	v_mfma_f32_32x32x16_bf16 v[2:17], v[78:81], v[232:235], v[2:17]
	s_waitcnt lgkmcnt(5)
	v_mfma_f32_32x32x16_bf16 v[34:49], v[94:97], v[70:73], v[34:49]
	v_add_u32_e32 v78, 0x124c0, v231
	v_add_u32_e32 v82, 0x124e0, v231
	ds_read_b128 v[78:81], v78
	ds_read_b128 v[82:85], v82
	s_waitcnt lgkmcnt(5)
	v_mfma_f32_32x32x16_bf16 v[18:33], v[94:97], v[66:69], v[18:33]
	s_waitcnt lgkmcnt(3)
	v_mfma_f32_32x32x16_bf16 v[2:17], v[94:97], v[102:105], v[2:17]
	ds_read_b128 v[66:69], v1 offset:35968
	ds_read_b128 v[70:73], v1 offset:36000
	ds_read_b128 v[86:89], v1 offset:36224
	ds_read_b128 v[94:97], v1 offset:36256
	v_mfma_f32_32x32x16_bf16 v[34:49], v[98:101], v[74:77], v[34:49]
	ds_read_b128 v[102:105], v1 offset:36480
	ds_read_b128 v[232:235], v1 offset:36512
	v_mfma_f32_32x32x16_bf16 v[18:33], v[98:101], v[90:93], v[18:33]
	s_waitcnt lgkmcnt(8)
	v_mfma_f32_32x32x16_bf16 v[2:17], v[98:101], v[242:245], v[2:17]
	s_waitcnt lgkmcnt(5)
	v_mfma_f32_32x32x16_bf16 v[34:49], v[78:81], v[66:69], v[34:49]
	v_add_u32_e32 v74, 0x12480, v231
	v_add_u32_e32 v90, 0x124a0, v231
	ds_read_b128 v[74:77], v74
	ds_read_b128 v[90:93], v90
	s_waitcnt lgkmcnt(5)
	v_mfma_f32_32x32x16_bf16 v[18:33], v[78:81], v[86:89], v[18:33]
	s_waitcnt lgkmcnt(3)
	v_mfma_f32_32x32x16_bf16 v[2:17], v[78:81], v[102:105], v[2:17]
	ds_read_b128 v[66:69], v1 offset:36160
	ds_read_b128 v[78:81], v1 offset:36192
	v_mfma_f32_32x32x16_bf16 v[34:49], v[82:85], v[70:73], v[34:49]
	ds_read_b128 v[86:89], v1 offset:36416
	ds_read_b128 v[98:101], v1 offset:36448
	v_mfma_f32_32x32x16_bf16 v[18:33], v[82:85], v[94:97], v[18:33]
	s_waitcnt lgkmcnt(6)
	v_mfma_f32_32x32x16_bf16 v[2:17], v[82:85], v[232:235], v[2:17]
	v_add_u32_e32 v70, 0x12440, v231
	v_add_u32_e32 v82, 0x12460, v231
	ds_read_b128 v[70:73], v70
	ds_read_b128 v[82:85], v82
	s_waitcnt lgkmcnt(5)
	v_mfma_f32_32x32x16_bf16 v[18:33], v[74:77], v[66:69], v[18:33]
	s_waitcnt lgkmcnt(3)
	v_mfma_f32_32x32x16_bf16 v[2:17], v[74:77], v[86:89], v[2:17]
	ds_read_b128 v[66:69], v1 offset:36096
	ds_read_b128 v[74:77], v1 offset:36128
	ds_read_b128 v[86:89], v1 offset:36352
	ds_read_b128 v[94:97], v1 offset:36384
	v_mfma_f32_32x32x16_bf16 v[18:33], v[90:93], v[78:81], v[18:33]
	s_waitcnt lgkmcnt(6)
	v_mfma_f32_32x32x16_bf16 v[2:17], v[90:93], v[98:101], v[2:17]
	v_add_u32_e32 v78, 0x12400, v231
	v_add_u32_e32 v90, 0x12420, v231
	ds_read_b128 v[78:81], v78
	ds_read_b128 v[90:93], v90
	s_waitcnt lgkmcnt(5)
	v_mfma_f32_32x32x16_bf16 v[18:33], v[70:73], v[66:69], v[18:33]
	s_waitcnt lgkmcnt(3)
	v_mfma_f32_32x32x16_bf16 v[2:17], v[70:73], v[86:89], v[2:17]
	ds_read_b128 v[66:69], v1 offset:36032
	ds_read_b128 v[70:73], v1 offset:36064
	ds_read_b128 v[86:89], v1 offset:36288
	ds_read_b128 v[98:101], v1 offset:36320
	v_mfma_f32_32x32x16_bf16 v[18:33], v[82:85], v[74:77], v[18:33]
	s_waitcnt lgkmcnt(6)
	v_mfma_f32_32x32x16_bf16 v[2:17], v[82:85], v[94:97], v[2:17]
	v_add_u32_e32 v74, 0x123c0, v231
	v_add_u32_e32 v82, 0x123e0, v231
	ds_read_b128 v[74:77], v74
	ds_read_b128 v[82:85], v82
	s_waitcnt lgkmcnt(5)
	v_mfma_f32_32x32x16_bf16 v[18:33], v[78:81], v[66:69], v[18:33]
	s_waitcnt lgkmcnt(3)
	v_mfma_f32_32x32x16_bf16 v[2:17], v[78:81], v[86:89], v[2:17]
	ds_read_b128 v[66:69], v1 offset:35968
	ds_read_b128 v[78:81], v1 offset:36000
	ds_read_b128 v[86:89], v1 offset:36224
	ds_read_b128 v[94:97], v1 offset:36256
	v_mfma_f32_32x32x16_bf16 v[18:33], v[90:93], v[70:73], v[18:33]
	s_waitcnt lgkmcnt(6)
	v_mfma_f32_32x32x16_bf16 v[2:17], v[90:93], v[98:101], v[2:17]
	v_add_u32_e32 v70, 0x12380, v231
	v_add_u32_e32 v90, 0x123a0, v231
	ds_read_b128 v[70:73], v70
	ds_read_b128 v[90:93], v90
	s_waitcnt lgkmcnt(5)
	v_mfma_f32_32x32x16_bf16 v[18:33], v[74:77], v[66:69], v[18:33]
	s_waitcnt lgkmcnt(3)
	v_mfma_f32_32x32x16_bf16 v[2:17], v[74:77], v[86:89], v[2:17]
	ds_read_b128 v[66:69], v1 offset:36160
	ds_read_b128 v[74:77], v1 offset:36192
	v_mfma_f32_32x32x16_bf16 v[18:33], v[82:85], v[78:81], v[18:33]
	s_waitcnt lgkmcnt(4)
	v_mfma_f32_32x32x16_bf16 v[2:17], v[82:85], v[94:97], v[2:17]
	v_add_u32_e32 v78, 0x12340, v231
	v_add_u32_e32 v82, 0x12360, v231
	ds_read_b128 v[78:81], v78
	ds_read_b128 v[82:85], v82
	s_waitcnt lgkmcnt(3)
	v_mfma_f32_32x32x16_bf16 v[2:17], v[70:73], v[66:69], v[2:17]
	ds_read_b128 v[66:69], v1 offset:36096
	ds_read_b128 v[70:73], v1 offset:36128
	s_waitcnt lgkmcnt(4)
	v_mfma_f32_32x32x16_bf16 v[2:17], v[90:93], v[74:77], v[2:17]
	v_add_u32_e32 v74, 0x12300, v231
	v_add_u32_e32 v86, 0x12320, v231
	ds_read_b128 v[74:77], v74
	ds_read_b128 v[86:89], v86
	s_waitcnt lgkmcnt(3)
	v_mfma_f32_32x32x16_bf16 v[2:17], v[78:81], v[66:69], v[2:17]
	ds_read_b128 v[66:69], v1 offset:36032
	ds_read_b128 v[78:81], v1 offset:36064
	s_waitcnt lgkmcnt(4)
	v_mfma_f32_32x32x16_bf16 v[2:17], v[82:85], v[70:73], v[2:17]
	v_add_u32_e32 v70, 0x122c0, v231
	v_add_u32_e32 v82, 0x122e0, v231
	ds_read_b128 v[70:73], v70
	ds_read_b128 v[82:85], v82
	s_waitcnt lgkmcnt(3)
	v_mfma_f32_32x32x16_bf16 v[2:17], v[74:77], v[66:69], v[2:17]
	ds_read_b128 v[66:69], v1 offset:35968
	ds_read_b128 v[74:77], v1 offset:36000
	s_waitcnt lgkmcnt(4)
	v_mfma_f32_32x32x16_bf16 v[2:17], v[86:89], v[78:81], v[2:17]
	s_waitcnt lgkmcnt(1)
	v_mfma_f32_32x32x16_bf16 v[2:17], v[70:73], v[66:69], v[2:17]
	s_and_b64 vcc, exec, s[70:71]
	s_waitcnt lgkmcnt(0)
	v_mfma_f32_32x32x16_bf16 v[2:17], v[82:85], v[74:77], v[2:17]
	s_cbranch_vccz .LBB0_710
	s_waitcnt vmcnt(0)
	v_mov_b32_e32 v68, v250
	v_mov_b32_e32 v74, v253
	v_mov_b32_e32 v78, v254
	v_mov_b32_e32 v76, v255
	v_lshlrev_b32_e32 v66, 16, v197
	v_cndmask_b32_e64 v67, 0, v66, s[80:81]
	v_lshlrev_b32_e32 v66, 16, v230
	v_readlane_b32 s10, v251, 10
	v_cndmask_b32_e64 v71, 0, v66, s[82:83]
	v_lshlrev_b32_e32 v66, 16, v229
	v_readlane_b32 s11, v251, 11
	v_lshlrev_b32_e32 v95, 16, v221
	v_lshlrev_b32_e32 v97, 16, v220
	v_cndmask_b32_e64 v73, 0, v66, s[10:11]
	v_readlane_b32 s10, v251, 12
	v_lshlrev_b32_e32 v66, 16, v228
	v_readlane_b32 s11, v251, 13
	v_lshlrev_b32_e32 v105, 16, v203
	v_lshlrev_b32_e32 v203, 16, v200
	v_cndmask_b32_e64 v81, 0, v66, s[10:11]
	v_readlane_b32 s10, v251, 14
	v_lshlrev_b32_e32 v66, 16, v227
	v_readlane_b32 s11, v251, 15
	v_and_b32_e32 v221, 16, v201
	v_and_b32_e32 v220, 0xffff0000, v200
	v_cndmask_b32_e64 v83, 0, v66, s[10:11]
	v_readlane_b32 s10, v251, 16
	v_lshlrev_b32_e32 v66, 16, v226
	v_readlane_b32 s11, v251, 17
	v_mov_b32_e32 v200, v220
	v_and_b32_e32 v104, 0xffff0000, v201
	v_cndmask_b32_e64 v85, 0, v66, s[10:11]
	v_readlane_b32 s10, v251, 18
	v_lshlrev_b32_e32 v66, 16, v225
	v_readlane_b32 s11, v251, 19
	v_lshlrev_b32_e32 v201, 16, v201
	v_lshlrev_b32_e32 v91, 16, v223
	v_cndmask_b32_e64 v87, 0, v66, s[10:11]
	v_readlane_b32 s10, v251, 20
	v_lshlrev_b32_e32 v66, 16, v224
	v_readlane_b32 s11, v251, 21
	v_lshlrev_b32_e32 v93, 16, v222
	v_pk_mov_b32 v[222:223], v[200:201], v[104:105] op_sel:[1,0]
	v_cndmask_b32_e64 v89, 0, v66, s[10:11]
	v_lshlrev_b32_e32 v66, 16, v202
	v_cndmask_b32_e64 v202, v66, 0, s[12:13]
	v_pk_mov_b32 v[220:221], v[202:203], v[220:221] op_sel:[1,0]
	s_lshl_b64 s[10:11], s[90:91], 15
	v_lshlrev_b32_e32 v101, 16, v205
	v_lshlrev_b32_e32 v103, 16, v204
	v_lshl_add_u64 v[204:205], v[162:163], 0, s[10:11]
	v_and_b32_e32 v102, 0xffff0000, v199
	v_and_b32_e32 v100, 0xffff0000, v133
	v_lshlrev_b32_e32 v99, 16, v219
	v_and_b32_e32 v98, 0xffff0000, v131
	v_and_b32_e32 v96, 0xffff0000, v129
	v_and_b32_e32 v94, 0xffff0000, v127
	v_and_b32_e32 v92, 0xffff0000, v125
	v_and_b32_e32 v90, 0xffff0000, v123
	v_and_b32_e32 v88, 0xffff0000, v121
	v_and_b32_e32 v86, 0xffff0000, v119
	v_and_b32_e32 v84, 0xffff0000, v117
	v_and_b32_e32 v82, 0xffff0000, v115
	v_and_b32_e32 v80, 0xffff0000, v113
	v_and_b32_e32 v72, 0xffff0000, v111
	v_and_b32_e32 v70, 0xffff0000, v109
	v_and_b32_e32 v66, 0xffff0000, v107
	s_waitcnt vmcnt(2)
	v_pk_mul_f32 v[220:221], v[74:75], v[220:221] op_sel_hi:[0,1]
	v_pk_fma_f32 v[202:203], v[68:69], v[202:203], v[220:221] op_sel_hi:[0,1,1]
	s_waitcnt vmcnt(1)
	v_pk_fma_f32 v[202:203], v[78:79], v[200:201], v[202:203] op_sel_hi:[0,1,1]
	s_waitcnt vmcnt(0)
	v_pk_add_f32 v[202:203], v[76:77], v[202:203] op_sel_hi:[0,1]
	v_pk_mul_f32 v[50:51], v[50:51], v[202:203]
	v_pk_mul_f32 v[202:203], v[74:75], v[222:223] op_sel_hi:[0,1]
	v_pk_fma_f32 v[200:201], v[68:69], v[200:201], v[202:203] op_sel_hi:[0,1,1]
	v_pk_fma_f32 v[104:105], v[78:79], v[104:105], v[200:201] op_sel_hi:[0,1,1]
	v_pk_add_f32 v[104:105], v[76:77], v[104:105] op_sel_hi:[0,1]
	v_pk_mul_f32 v[52:53], v[52:53], v[104:105]
	v_cvt_pk_bf16_f32 v104, v50, v51
	v_cvt_pk_bf16_f32 v105, v52, v53
	v_lshl_add_u64 v[50:51], v[204:205], 0, v[136:137]
	global_store_dwordx2 v[50:51], v[104:105], off
	v_and_b32_e32 v53, 16, v199
	v_and_b32_e32 v52, 0xffff0000, v198
	v_lshlrev_b32_e32 v105, 16, v199
	v_lshlrev_b32_e32 v199, 16, v198
	v_lshlrev_b32_e32 v198, 16, v195
	v_mov_b32_e32 v104, v52
	v_pk_mov_b32 v[52:53], v[198:199], v[52:53] op_sel:[1,0]
	v_pk_mov_b32 v[200:201], v[104:105], v[102:103] op_sel:[1,0]
	v_pk_mul_f32 v[52:53], v[74:75], v[52:53] op_sel_hi:[0,1]
	v_pk_fma_f32 v[52:53], v[68:69], v[198:199], v[52:53] op_sel_hi:[0,1,1]
	v_pk_fma_f32 v[52:53], v[78:79], v[104:105], v[52:53] op_sel_hi:[0,1,1]
	v_pk_add_f32 v[52:53], v[76:77], v[52:53] op_sel_hi:[0,1]
	v_pk_mul_f32 v[52:53], v[54:55], v[52:53]
	v_pk_mul_f32 v[54:55], v[74:75], v[200:201] op_sel_hi:[0,1]
	v_pk_fma_f32 v[54:55], v[68:69], v[104:105], v[54:55] op_sel_hi:[0,1,1]
	v_pk_fma_f32 v[54:55], v[78:79], v[102:103], v[54:55] op_sel_hi:[0,1,1]
	v_pk_add_f32 v[54:55], v[76:77], v[54:55] op_sel_hi:[0,1]
	v_pk_mul_f32 v[54:55], v[56:57], v[54:55]
	v_cvt_pk_bf16_f32 v52, v52, v53
	v_cvt_pk_bf16_f32 v53, v54, v55
	global_store_dwordx2 v[50:51], v[52:53], off offset:16
	v_and_b32_e32 v53, 16, v133
	v_and_b32_e32 v52, 0xffff0000, v132
	v_lshlrev_b32_e32 v103, 16, v132
	v_lshlrev_b32_e32 v102, 16, v193
	v_lshlrev_b32_e32 v55, 16, v133
	v_mov_b32_e32 v54, v52
	v_pk_mov_b32 v[52:53], v[102:103], v[52:53] op_sel:[1,0]
	v_pk_mov_b32 v[56:57], v[54:55], v[100:101] op_sel:[1,0]
	v_pk_mul_f32 v[52:53], v[74:75], v[52:53] op_sel_hi:[0,1]
	v_pk_fma_f32 v[52:53], v[68:69], v[102:103], v[52:53] op_sel_hi:[0,1,1]
	v_pk_mul_f32 v[56:57], v[74:75], v[56:57] op_sel_hi:[0,1]
	v_pk_fma_f32 v[52:53], v[78:79], v[54:55], v[52:53] op_sel_hi:[0,1,1]
	v_pk_fma_f32 v[54:55], v[68:69], v[54:55], v[56:57] op_sel_hi:[0,1,1]
	v_pk_fma_f32 v[54:55], v[78:79], v[100:101], v[54:55] op_sel_hi:[0,1,1]
	v_pk_add_f32 v[52:53], v[76:77], v[52:53] op_sel_hi:[0,1]
	v_pk_add_f32 v[54:55], v[76:77], v[54:55] op_sel_hi:[0,1]
	v_pk_mul_f32 v[52:53], v[58:59], v[52:53]
	v_pk_mul_f32 v[54:55], v[60:61], v[54:55]
	v_cvt_pk_bf16_f32 v52, v52, v53
	v_cvt_pk_bf16_f32 v53, v54, v55
	global_store_dwordx2 v[50:51], v[52:53], off offset:32
	v_and_b32_e32 v53, 16, v131
	v_and_b32_e32 v52, 0xffff0000, v130
	v_lshlrev_b32_e32 v59, 16, v130
	v_lshlrev_b32_e32 v58, 16, v191
	v_lshlrev_b32_e32 v55, 16, v131
	v_mov_b32_e32 v54, v52
	v_pk_mov_b32 v[52:53], v[58:59], v[52:53] op_sel:[1,0]
	v_pk_mov_b32 v[56:57], v[54:55], v[98:99] op_sel:[1,0]
	v_pk_mul_f32 v[52:53], v[74:75], v[52:53] op_sel_hi:[0,1]
	v_pk_fma_f32 v[52:53], v[68:69], v[58:59], v[52:53] op_sel_hi:[0,1,1]
	v_pk_mul_f32 v[56:57], v[74:75], v[56:57] op_sel_hi:[0,1]
	v_pk_fma_f32 v[52:53], v[78:79], v[54:55], v[52:53] op_sel_hi:[0,1,1]
	v_pk_fma_f32 v[54:55], v[68:69], v[54:55], v[56:57] op_sel_hi:[0,1,1]
	v_pk_fma_f32 v[54:55], v[78:79], v[98:99], v[54:55] op_sel_hi:[0,1,1]
	v_pk_add_f32 v[52:53], v[76:77], v[52:53] op_sel_hi:[0,1]
	v_pk_add_f32 v[54:55], v[76:77], v[54:55] op_sel_hi:[0,1]
	v_pk_mul_f32 v[52:53], v[62:63], v[52:53]
	v_pk_mul_f32 v[54:55], v[64:65], v[54:55]
	v_cvt_pk_bf16_f32 v52, v52, v53
	v_cvt_pk_bf16_f32 v53, v54, v55
	global_store_dwordx2 v[50:51], v[52:53], off offset:48
	v_and_b32_e32 v53, 16, v129
	v_and_b32_e32 v52, 0xffff0000, v128
	v_lshlrev_b32_e32 v59, 16, v128
	v_lshlrev_b32_e32 v58, 16, v189
	v_mov_b32_e32 v54, v52
	v_pk_mov_b32 v[52:53], v[58:59], v[52:53] op_sel:[1,0]
	v_lshlrev_b32_e32 v55, 16, v129
	v_pk_mul_f32 v[52:53], v[74:75], v[52:53] op_sel_hi:[0,1]
	v_pk_fma_f32 v[52:53], v[68:69], v[58:59], v[52:53] op_sel_hi:[0,1,1]
	v_pk_fma_f32 v[52:53], v[78:79], v[54:55], v[52:53] op_sel_hi:[0,1,1]
	v_pk_mov_b32 v[56:57], v[54:55], v[96:97] op_sel:[1,0]
	v_pk_add_f32 v[52:53], v[76:77], v[52:53] op_sel_hi:[0,1]
	v_pk_mul_f32 v[34:35], v[34:35], v[52:53]
	v_pk_mul_f32 v[52:53], v[74:75], v[56:57] op_sel_hi:[0,1]
	v_pk_fma_f32 v[52:53], v[68:69], v[54:55], v[52:53] op_sel_hi:[0,1,1]
	v_pk_fma_f32 v[52:53], v[78:79], v[96:97], v[52:53] op_sel_hi:[0,1,1]
	v_pk_add_f32 v[52:53], v[76:77], v[52:53] op_sel_hi:[0,1]
	v_pk_mul_f32 v[36:37], v[36:37], v[52:53]
	v_cvt_pk_bf16_f32 v34, v34, v35
	v_cvt_pk_bf16_f32 v35, v36, v37
	global_store_dwordx2 v[50:51], v[34:35], off offset:256
	v_and_b32_e32 v35, 16, v127
	v_and_b32_e32 v34, 0xffff0000, v126
	v_lshlrev_b32_e32 v55, 16, v126
	v_lshlrev_b32_e32 v54, 16, v187
	v_mov_b32_e32 v36, v34
	v_pk_mov_b32 v[34:35], v[54:55], v[34:35] op_sel:[1,0]
	v_lshlrev_b32_e32 v37, 16, v127
	v_pk_mul_f32 v[34:35], v[74:75], v[34:35] op_sel_hi:[0,1]
	v_pk_fma_f32 v[34:35], v[68:69], v[54:55], v[34:35] op_sel_hi:[0,1,1]
	v_pk_fma_f32 v[34:35], v[78:79], v[36:37], v[34:35] op_sel_hi:[0,1,1]
	v_pk_mov_b32 v[52:53], v[36:37], v[94:95] op_sel:[1,0]
	v_pk_add_f32 v[34:35], v[76:77], v[34:35] op_sel_hi:[0,1]
	v_pk_mul_f32 v[34:35], v[38:39], v[34:35]
	v_pk_mul_f32 v[38:39], v[74:75], v[52:53] op_sel_hi:[0,1]
	v_pk_fma_f32 v[36:37], v[68:69], v[36:37], v[38:39] op_sel_hi:[0,1,1]
	v_pk_fma_f32 v[36:37], v[78:79], v[94:95], v[36:37] op_sel_hi:[0,1,1]
	v_pk_add_f32 v[36:37], v[76:77], v[36:37] op_sel_hi:[0,1]
	v_pk_mul_f32 v[36:37], v[40:41], v[36:37]
	v_cvt_pk_bf16_f32 v34, v34, v35
	v_cvt_pk_bf16_f32 v35, v36, v37
	global_store_dwordx2 v[50:51], v[34:35], off offset:272
	v_and_b32_e32 v35, 16, v125
	v_and_b32_e32 v34, 0xffff0000, v124
	v_lshlrev_b32_e32 v41, 16, v124
	v_lshlrev_b32_e32 v40, 16, v185
	v_lshlrev_b32_e32 v37, 16, v125
	v_mov_b32_e32 v36, v34
	v_pk_mov_b32 v[34:35], v[40:41], v[34:35] op_sel:[1,0]
	v_pk_mov_b32 v[38:39], v[36:37], v[92:93] op_sel:[1,0]
	v_pk_mul_f32 v[34:35], v[74:75], v[34:35] op_sel_hi:[0,1]
	v_pk_fma_f32 v[34:35], v[68:69], v[40:41], v[34:35] op_sel_hi:[0,1,1]
	v_pk_mul_f32 v[38:39], v[74:75], v[38:39] op_sel_hi:[0,1]
	v_pk_fma_f32 v[34:35], v[78:79], v[36:37], v[34:35] op_sel_hi:[0,1,1]
	v_pk_fma_f32 v[36:37], v[68:69], v[36:37], v[38:39] op_sel_hi:[0,1,1]
	v_pk_fma_f32 v[36:37], v[78:79], v[92:93], v[36:37] op_sel_hi:[0,1,1]
	v_pk_add_f32 v[34:35], v[76:77], v[34:35] op_sel_hi:[0,1]
	v_pk_add_f32 v[36:37], v[76:77], v[36:37] op_sel_hi:[0,1]
	v_pk_mul_f32 v[34:35], v[42:43], v[34:35]
	v_pk_mul_f32 v[36:37], v[44:45], v[36:37]
	v_cvt_pk_bf16_f32 v34, v34, v35
	v_cvt_pk_bf16_f32 v35, v36, v37
	global_store_dwordx2 v[50:51], v[34:35], off offset:288
	v_and_b32_e32 v35, 16, v123
	v_and_b32_e32 v34, 0xffff0000, v122
	v_lshlrev_b32_e32 v41, 16, v122
	v_lshlrev_b32_e32 v40, 16, v183
	v_lshlrev_b32_e32 v37, 16, v123
	v_mov_b32_e32 v36, v34
	v_pk_mov_b32 v[34:35], v[40:41], v[34:35] op_sel:[1,0]
	v_pk_mov_b32 v[38:39], v[36:37], v[90:91] op_sel:[1,0]
	v_pk_mul_f32 v[34:35], v[74:75], v[34:35] op_sel_hi:[0,1]
	v_pk_fma_f32 v[34:35], v[68:69], v[40:41], v[34:35] op_sel_hi:[0,1,1]
	v_pk_mul_f32 v[38:39], v[74:75], v[38:39] op_sel_hi:[0,1]
	v_pk_fma_f32 v[34:35], v[78:79], v[36:37], v[34:35] op_sel_hi:[0,1,1]
	v_pk_fma_f32 v[36:37], v[68:69], v[36:37], v[38:39] op_sel_hi:[0,1,1]
	v_pk_fma_f32 v[36:37], v[78:79], v[90:91], v[36:37] op_sel_hi:[0,1,1]
	v_pk_add_f32 v[34:35], v[76:77], v[34:35] op_sel_hi:[0,1]
	v_pk_add_f32 v[36:37], v[76:77], v[36:37] op_sel_hi:[0,1]
	v_pk_mul_f32 v[34:35], v[46:47], v[34:35]
	v_pk_mul_f32 v[36:37], v[48:49], v[36:37]
	v_cvt_pk_bf16_f32 v34, v34, v35
	v_cvt_pk_bf16_f32 v35, v36, v37
	global_store_dwordx2 v[50:51], v[34:35], off offset:304
	v_and_b32_e32 v35, 16, v121
	v_and_b32_e32 v34, 0xffff0000, v120
	v_lshlrev_b32_e32 v41, 16, v120
	v_lshlrev_b32_e32 v40, 16, v181
	v_mov_b32_e32 v36, v34
	v_pk_mov_b32 v[34:35], v[40:41], v[34:35] op_sel:[1,0]
	v_lshlrev_b32_e32 v37, 16, v121
	v_pk_mul_f32 v[34:35], v[74:75], v[34:35] op_sel_hi:[0,1]
	v_pk_fma_f32 v[34:35], v[68:69], v[40:41], v[34:35] op_sel_hi:[0,1,1]
	v_pk_fma_f32 v[34:35], v[78:79], v[36:37], v[34:35] op_sel_hi:[0,1,1]
	v_pk_mov_b32 v[38:39], v[36:37], v[88:89] op_sel:[1,0]
	v_pk_add_f32 v[34:35], v[76:77], v[34:35] op_sel_hi:[0,1]
	v_pk_mul_f32 v[18:19], v[18:19], v[34:35]
	v_pk_mul_f32 v[34:35], v[74:75], v[38:39] op_sel_hi:[0,1]
	v_pk_fma_f32 v[34:35], v[68:69], v[36:37], v[34:35] op_sel_hi:[0,1,1]
	v_pk_fma_f32 v[34:35], v[78:79], v[88:89], v[34:35] op_sel_hi:[0,1,1]
	v_pk_add_f32 v[34:35], v[76:77], v[34:35] op_sel_hi:[0,1]
	v_pk_mul_f32 v[20:21], v[20:21], v[34:35]
	v_cvt_pk_bf16_f32 v18, v18, v19
	v_cvt_pk_bf16_f32 v19, v20, v21
	global_store_dwordx2 v[50:51], v[18:19], off offset:512
	v_and_b32_e32 v19, 16, v119
	v_and_b32_e32 v18, 0xffff0000, v118
	v_lshlrev_b32_e32 v37, 16, v118
	v_lshlrev_b32_e32 v36, 16, v177
	v_mov_b32_e32 v20, v18
	v_pk_mov_b32 v[18:19], v[36:37], v[18:19] op_sel:[1,0]
	v_lshlrev_b32_e32 v21, 16, v119
	v_pk_mul_f32 v[18:19], v[74:75], v[18:19] op_sel_hi:[0,1]
	v_pk_fma_f32 v[18:19], v[68:69], v[36:37], v[18:19] op_sel_hi:[0,1,1]
	v_pk_fma_f32 v[18:19], v[78:79], v[20:21], v[18:19] op_sel_hi:[0,1,1]
	v_pk_mov_b32 v[34:35], v[20:21], v[86:87] op_sel:[1,0]
	v_pk_add_f32 v[18:19], v[76:77], v[18:19] op_sel_hi:[0,1]
	v_pk_mul_f32 v[18:19], v[22:23], v[18:19]
	v_pk_mul_f32 v[22:23], v[74:75], v[34:35] op_sel_hi:[0,1]
	v_pk_fma_f32 v[20:21], v[68:69], v[20:21], v[22:23] op_sel_hi:[0,1,1]
	v_pk_fma_f32 v[20:21], v[78:79], v[86:87], v[20:21] op_sel_hi:[0,1,1]
	v_pk_add_f32 v[20:21], v[76:77], v[20:21] op_sel_hi:[0,1]
	v_pk_mul_f32 v[20:21], v[24:25], v[20:21]
	v_cvt_pk_bf16_f32 v18, v18, v19
	v_cvt_pk_bf16_f32 v19, v20, v21
	global_store_dwordx2 v[50:51], v[18:19], off offset:528
	v_and_b32_e32 v19, 16, v117
	v_and_b32_e32 v18, 0xffff0000, v116
	v_lshlrev_b32_e32 v25, 16, v116
	v_lshlrev_b32_e32 v24, 16, v175
	v_lshlrev_b32_e32 v21, 16, v117
	v_mov_b32_e32 v20, v18
	v_pk_mov_b32 v[18:19], v[24:25], v[18:19] op_sel:[1,0]
	v_pk_mov_b32 v[22:23], v[20:21], v[84:85] op_sel:[1,0]
	v_pk_mul_f32 v[18:19], v[74:75], v[18:19] op_sel_hi:[0,1]
	v_pk_fma_f32 v[18:19], v[68:69], v[24:25], v[18:19] op_sel_hi:[0,1,1]
	v_pk_mul_f32 v[22:23], v[74:75], v[22:23] op_sel_hi:[0,1]
	v_pk_fma_f32 v[18:19], v[78:79], v[20:21], v[18:19] op_sel_hi:[0,1,1]
	v_pk_fma_f32 v[20:21], v[68:69], v[20:21], v[22:23] op_sel_hi:[0,1,1]
	v_pk_fma_f32 v[20:21], v[78:79], v[84:85], v[20:21] op_sel_hi:[0,1,1]
	v_pk_add_f32 v[18:19], v[76:77], v[18:19] op_sel_hi:[0,1]
	v_pk_add_f32 v[20:21], v[76:77], v[20:21] op_sel_hi:[0,1]
	v_pk_mul_f32 v[18:19], v[26:27], v[18:19]
	v_pk_mul_f32 v[20:21], v[28:29], v[20:21]
	v_cvt_pk_bf16_f32 v18, v18, v19
	v_cvt_pk_bf16_f32 v19, v20, v21
	global_store_dwordx2 v[50:51], v[18:19], off offset:544
	v_and_b32_e32 v19, 16, v115
	v_and_b32_e32 v18, 0xffff0000, v114
	v_lshlrev_b32_e32 v25, 16, v114
	v_lshlrev_b32_e32 v24, 16, v173
	v_lshlrev_b32_e32 v21, 16, v115
	v_mov_b32_e32 v20, v18
	v_pk_mov_b32 v[18:19], v[24:25], v[18:19] op_sel:[1,0]
	v_pk_mov_b32 v[22:23], v[20:21], v[82:83] op_sel:[1,0]
	v_pk_mul_f32 v[18:19], v[74:75], v[18:19] op_sel_hi:[0,1]
	v_pk_fma_f32 v[18:19], v[68:69], v[24:25], v[18:19] op_sel_hi:[0,1,1]
	v_pk_mul_f32 v[22:23], v[74:75], v[22:23] op_sel_hi:[0,1]
	v_pk_fma_f32 v[18:19], v[78:79], v[20:21], v[18:19] op_sel_hi:[0,1,1]
	v_pk_fma_f32 v[20:21], v[68:69], v[20:21], v[22:23] op_sel_hi:[0,1,1]
	v_pk_fma_f32 v[20:21], v[78:79], v[82:83], v[20:21] op_sel_hi:[0,1,1]
	v_pk_add_f32 v[18:19], v[76:77], v[18:19] op_sel_hi:[0,1]
	v_pk_add_f32 v[20:21], v[76:77], v[20:21] op_sel_hi:[0,1]
	v_pk_mul_f32 v[18:19], v[30:31], v[18:19]
	v_pk_mul_f32 v[20:21], v[32:33], v[20:21]
	v_cvt_pk_bf16_f32 v18, v18, v19
	v_cvt_pk_bf16_f32 v19, v20, v21
	global_store_dwordx2 v[50:51], v[18:19], off offset:560
	v_and_b32_e32 v19, 16, v113
	v_and_b32_e32 v18, 0xffff0000, v112
	v_lshlrev_b32_e32 v25, 16, v112
	v_lshlrev_b32_e32 v24, 16, v171
	v_mov_b32_e32 v20, v18
	v_pk_mov_b32 v[18:19], v[24:25], v[18:19] op_sel:[1,0]
	v_lshlrev_b32_e32 v21, 16, v113
	v_pk_mul_f32 v[18:19], v[74:75], v[18:19] op_sel_hi:[0,1]
	v_pk_fma_f32 v[18:19], v[68:69], v[24:25], v[18:19] op_sel_hi:[0,1,1]
	v_pk_fma_f32 v[18:19], v[78:79], v[20:21], v[18:19] op_sel_hi:[0,1,1]
	v_pk_mov_b32 v[22:23], v[20:21], v[80:81] op_sel:[1,0]
	v_pk_add_f32 v[18:19], v[76:77], v[18:19] op_sel_hi:[0,1]
	v_pk_mul_f32 v[2:3], v[2:3], v[18:19]
	v_pk_mul_f32 v[18:19], v[74:75], v[22:23] op_sel_hi:[0,1]
	v_pk_fma_f32 v[18:19], v[68:69], v[20:21], v[18:19] op_sel_hi:[0,1,1]
	v_pk_fma_f32 v[18:19], v[78:79], v[80:81], v[18:19] op_sel_hi:[0,1,1]
	v_pk_add_f32 v[18:19], v[76:77], v[18:19] op_sel_hi:[0,1]
	v_pk_mul_f32 v[4:5], v[4:5], v[18:19]
	v_cvt_pk_bf16_f32 v2, v2, v3
	v_cvt_pk_bf16_f32 v3, v4, v5
	global_store_dwordx2 v[50:51], v[2:3], off offset:768
	v_and_b32_e32 v3, 16, v111
	v_and_b32_e32 v2, 0xffff0000, v110
	v_lshlrev_b32_e32 v21, 16, v110
	v_lshlrev_b32_e32 v20, 16, v169
	v_mov_b32_e32 v4, v2
	v_pk_mov_b32 v[2:3], v[20:21], v[2:3] op_sel:[1,0]
	v_lshlrev_b32_e32 v5, 16, v111
	v_pk_mul_f32 v[2:3], v[74:75], v[2:3] op_sel_hi:[0,1]
	v_pk_fma_f32 v[2:3], v[68:69], v[20:21], v[2:3] op_sel_hi:[0,1,1]
	v_pk_fma_f32 v[2:3], v[78:79], v[4:5], v[2:3] op_sel_hi:[0,1,1]
	v_pk_mov_b32 v[18:19], v[4:5], v[72:73] op_sel:[1,0]
	v_pk_add_f32 v[2:3], v[76:77], v[2:3] op_sel_hi:[0,1]
	v_pk_mul_f32 v[2:3], v[6:7], v[2:3]
	v_pk_mul_f32 v[6:7], v[74:75], v[18:19] op_sel_hi:[0,1]
	v_pk_fma_f32 v[4:5], v[68:69], v[4:5], v[6:7] op_sel_hi:[0,1,1]
	v_pk_fma_f32 v[4:5], v[78:79], v[72:73], v[4:5] op_sel_hi:[0,1,1]
	v_pk_add_f32 v[4:5], v[76:77], v[4:5] op_sel_hi:[0,1]
	v_pk_mul_f32 v[4:5], v[8:9], v[4:5]
	v_cvt_pk_bf16_f32 v2, v2, v3
	v_cvt_pk_bf16_f32 v3, v4, v5
	global_store_dwordx2 v[50:51], v[2:3], off offset:784
	v_and_b32_e32 v3, 16, v109
	v_and_b32_e32 v2, 0xffff0000, v108
	v_lshlrev_b32_e32 v9, 16, v108
	v_lshlrev_b32_e32 v8, 16, v167
	v_lshlrev_b32_e32 v5, 16, v109
	v_mov_b32_e32 v4, v2
	v_pk_mov_b32 v[2:3], v[8:9], v[2:3] op_sel:[1,0]
	v_pk_mov_b32 v[6:7], v[4:5], v[70:71] op_sel:[1,0]
	v_pk_mul_f32 v[2:3], v[74:75], v[2:3] op_sel_hi:[0,1]
	v_pk_fma_f32 v[2:3], v[68:69], v[8:9], v[2:3] op_sel_hi:[0,1,1]
	v_pk_mul_f32 v[6:7], v[74:75], v[6:7] op_sel_hi:[0,1]
	v_pk_fma_f32 v[2:3], v[78:79], v[4:5], v[2:3] op_sel_hi:[0,1,1]
	v_pk_fma_f32 v[4:5], v[68:69], v[4:5], v[6:7] op_sel_hi:[0,1,1]
	v_pk_fma_f32 v[4:5], v[78:79], v[70:71], v[4:5] op_sel_hi:[0,1,1]
	v_pk_add_f32 v[2:3], v[76:77], v[2:3] op_sel_hi:[0,1]
	v_pk_add_f32 v[4:5], v[76:77], v[4:5] op_sel_hi:[0,1]
	v_pk_mul_f32 v[2:3], v[10:11], v[2:3]
	v_pk_mul_f32 v[4:5], v[12:13], v[4:5]
	v_cvt_pk_bf16_f32 v2, v2, v3
	v_cvt_pk_bf16_f32 v3, v4, v5
	global_store_dwordx2 v[50:51], v[2:3], off offset:800
	v_and_b32_e32 v3, 16, v107
	v_and_b32_e32 v2, 0xffff0000, v106
	v_lshlrev_b32_e32 v9, 16, v106
	v_lshlrev_b32_e32 v8, 16, v165
	v_lshlrev_b32_e32 v5, 16, v107
	v_mov_b32_e32 v4, v2
	v_pk_mov_b32 v[2:3], v[8:9], v[2:3] op_sel:[1,0]
	v_pk_mov_b32 v[6:7], v[4:5], v[66:67] op_sel:[1,0]
	v_pk_mul_f32 v[2:3], v[74:75], v[2:3] op_sel_hi:[0,1]
	v_pk_fma_f32 v[2:3], v[68:69], v[8:9], v[2:3] op_sel_hi:[0,1,1]
	v_pk_mul_f32 v[6:7], v[74:75], v[6:7] op_sel_hi:[0,1]
	v_pk_fma_f32 v[2:3], v[78:79], v[4:5], v[2:3] op_sel_hi:[0,1,1]
	v_pk_fma_f32 v[4:5], v[68:69], v[4:5], v[6:7] op_sel_hi:[0,1,1]
	v_pk_fma_f32 v[4:5], v[78:79], v[66:67], v[4:5] op_sel_hi:[0,1,1]
	v_pk_add_f32 v[2:3], v[76:77], v[2:3] op_sel_hi:[0,1]
	v_pk_add_f32 v[4:5], v[76:77], v[4:5] op_sel_hi:[0,1]
	v_pk_mul_f32 v[2:3], v[14:15], v[2:3]
	v_pk_mul_f32 v[4:5], v[16:17], v[4:5]
	v_cvt_pk_bf16_f32 v2, v2, v3
	v_cvt_pk_bf16_f32 v3, v4, v5
	global_store_dwordx2 v[50:51], v[2:3], off offset:816

	.amdhsa_kernel _Z6mk_fwd4Args
		.amdhsa_group_segment_fixed_size 0
		.amdhsa_private_segment_fixed_size 0
		.amdhsa_kernarg_size 528
		.amdhsa_user_sgpr_count 2
		.amdhsa_user_sgpr_dispatch_ptr 0
		.amdhsa_user_sgpr_queue_ptr 0
		.amdhsa_user_sgpr_kernarg_segment_ptr 1
		.amdhsa_user_sgpr_dispatch_id 0
		.amdhsa_user_sgpr_kernarg_preload_length 0
		.amdhsa_user_sgpr_kernarg_preload_offset 0
		.amdhsa_user_sgpr_private_segment_size 0
		.amdhsa_uses_dynamic_stack 0
		.amdhsa_enable_private_segment 0
		.amdhsa_system_sgpr_workgroup_id_x 1
		.amdhsa_system_sgpr_workgroup_id_y 0
		.amdhsa_system_sgpr_workgroup_id_z 0
		.amdhsa_system_sgpr_workgroup_info 0
		.amdhsa_system_vgpr_workitem_id 0
		.amdhsa_next_free_vgpr 256
		.amdhsa_next_free_sgpr 102
		.amdhsa_accum_offset 256
		.amdhsa_reserve_vcc 1
		.amdhsa_float_round_mode_32 0
		.amdhsa_float_round_mode_16_64 0
		.amdhsa_float_denorm_mode_32 3
		.amdhsa_float_denorm_mode_16_64 3
		.amdhsa_dx10_clamp 1
		.amdhsa_ieee_mode 1
		.amdhsa_fp16_overflow 0
		.amdhsa_tg_split 0
		.amdhsa_exception_fp_ieee_invalid_op 0
		.amdhsa_exception_fp_denorm_src 0
		.amdhsa_exception_fp_ieee_div_zero 0
		.amdhsa_exception_fp_ieee_overflow 0
		.amdhsa_exception_fp_ieee_underflow 0
		.amdhsa_exception_fp_ieee_inexact 0
		.amdhsa_exception_int_div_zero 0
	.end_amdhsa_kernel

amdhsa.kernels:
  - .agpr_count:     0
    .args:
      - .offset:         0
        .size:           272
        .value_kind:     by_value
      - .offset:         272
        .size:           4
        .value_kind:     hidden_block_count_x
      - .offset:         276
        .size:           4
        .value_kind:     hidden_block_count_y
      - .offset:         280
        .size:           4
        .value_kind:     hidden_block_count_z
      - .offset:         284
        .size:           2
        .value_kind:     hidden_group_size_x
      - .offset:         286
        .size:           2
        .value_kind:     hidden_group_size_y
      - .offset:         288
        .size:           2
        .value_kind:     hidden_group_size_z
      - .offset:         290
        .size:           2
        .value_kind:     hidden_remainder_x
      - .offset:         292
        .size:           2
        .value_kind:     hidden_remainder_y
      - .offset:         294
        .size:           2
        .value_kind:     hidden_remainder_z
      - .offset:         312
        .size:           8
        .value_kind:     hidden_global_offset_x
      - .offset:         320
        .size:           8
        .value_kind:     hidden_global_offset_y
      - .offset:         328
        .size:           8
        .value_kind:     hidden_global_offset_z
      - .offset:         336
        .size:           2
        .value_kind:     hidden_grid_dims
      - .offset:         392
        .size:           4
        .value_kind:     hidden_dynamic_lds_size
    .group_segment_fixed_size: 0
    .kernarg_segment_align: 8
    .kernarg_segment_size: 528
    .language:       OpenCL C
    .language_version:
      - 2
      - 0
    .max_flat_workgroup_size: 512
    .name:           _Z6mk_fwd4Args
    .private_segment_fixed_size: 0
    .sgpr_count:     108
    .sgpr_spill_count: 270
    .symbol:         _Z6mk_fwd4Args.kd
    .uniform_work_group_size: 1
    .uses_dynamic_stack: false
    .vgpr_count:     256
    .vgpr_spill_count: 0
    .wavefront_size: 64
